# plus B/C: accumulator-init tuple rebuilt only when the running max changed (branch on existing uniform test; 8 v_mov_b64 or nothing instead of 16 v_cndmask)
# speedup vs baseline: 1.0201x; 1.0031x over previous
; __device__ __forceinline__ void qkt12_roll(f32x16& p0, f32x16& p1, const f32x16& negm, int kb, int qa, const bf16x8* qr) {
;   const int a0 = kb ^ (0 << 5); const bf16x8 x0 = lds_rd128<0>(a0), y0 = lds_rd128<12288>(a0);
;   const int a1 = kb ^ (1 << 5); const bf16x8 x1 = lds_rd128<0>(a1), y1 = lds_rd128<12288>(a1);
;   asm volatile("s_waitcnt lgkmcnt(2)" ::: "memory"); SBAR();
;   p0 = __builtin_amdgcn_mfma_f32_32x32x16_bf16(x0, qr[0], negm, 0, 0, 0); p1 = __builtin_amdgcn_mfma_f32_32x32x16_bf16(y0, qr[0], negm, 0, 0, 0);
;   const int a2 = kb ^ (2 << 5); const bf16x8 x2 = lds_rd128<0>(a2), y2 = lds_rd128<12288>(a2);
;   asm volatile("s_waitcnt lgkmcnt(2)" ::: "memory"); SBAR();
;   p0 = __builtin_amdgcn_mfma_f32_32x32x16_bf16(x1, qr[1], p0, 0, 0, 0); p1 = __builtin_amdgcn_mfma_f32_32x32x16_bf16(y1, qr[1], p1, 0, 0, 0);
;   const int a3 = kb ^ (3 << 5); const bf16x8 x3 = lds_rd128<0>(a3), y3 = lds_rd128<12288>(a3);
;   asm volatile("s_waitcnt lgkmcnt(2)" ::: "memory"); SBAR();
;   p0 = __builtin_amdgcn_mfma_f32_32x32x16_bf16(x2, qr[2], p0, 0, 0, 0); p1 = __builtin_amdgcn_mfma_f32_32x32x16_bf16(y2, qr[2], p1, 0, 0, 0);
;   const int a4 = kb ^ (0 << 5); const bf16x8 x4 = lds_rd128<128>(a4), y4 = lds_rd128<12416>(a4);
;   asm volatile("s_waitcnt lgkmcnt(2)" ::: "memory"); SBAR();
;   p0 = __builtin_amdgcn_mfma_f32_32x32x16_bf16(x3, qr[3], p0, 0, 0, 0); p1 = __builtin_amdgcn_mfma_f32_32x32x16_bf16(y3, qr[3], p1, 0, 0, 0);
;   const int a5 = kb ^ (1 << 5); const bf16x8 x5 = lds_rd128<128>(a5), y5 = lds_rd128<12416>(a5);
;   asm volatile("s_waitcnt lgkmcnt(2)" ::: "memory"); SBAR();
;   p0 = __builtin_amdgcn_mfma_f32_32x32x16_bf16(x4, qr[4], p0, 0, 0, 0); p1 = __builtin_amdgcn_mfma_f32_32x32x16_bf16(y4, qr[4], p1, 0, 0, 0);
;   const int a6 = kb ^ (2 << 5); const bf16x8 x6 = lds_rd128<128>(a6), y6 = lds_rd128<12416>(a6);
;   asm volatile("s_waitcnt lgkmcnt(2)" ::: "memory"); SBAR();
;   p0 = __builtin_amdgcn_mfma_f32_32x32x16_bf16(x5, qr[5], p0, 0, 0, 0); p1 = __builtin_amdgcn_mfma_f32_32x32x16_bf16(y5, qr[5], p1, 0, 0, 0);
;   const int a7 = kb ^ (3 << 5); const bf16x8 x7 = lds_rd128<128>(a7), y7 = lds_rd128<12416>(a7);
;   asm volatile("s_waitcnt lgkmcnt(2)" ::: "memory"); SBAR();
;   p0 = __builtin_amdgcn_mfma_f32_32x32x16_bf16(x6, qr[6], p0, 0, 0, 0); p1 = __builtin_amdgcn_mfma_f32_32x32x16_bf16(y6, qr[6], p1, 0, 0, 0);
.LBB0_360:
	v_exp_f32_e32 v66, v66
	v_exp_f32_e32 v67, v67
	v_exp_f32_e32 v68, v68
	v_exp_f32_e32 v69, v69
	v_exp_f32_e32 v70, v70
	v_exp_f32_e32 v71, v71
	v_exp_f32_e32 v72, v72
	v_exp_f32_e32 v73, v73
	v_add_f32_e32 v98, v148, v146
	v_add_f32_e32 v99, v159, v161
	v_add_f32_e32 v100, v149, v147
	v_add_f32_e32 v101, v158, v160
	v_exp_f32_e32 v74, v74
	v_exp_f32_e32 v75, v75
	v_exp_f32_e32 v76, v76
	v_exp_f32_e32 v77, v77
	v_add_f32_e32 v98, v150, v98
	v_add_f32_e32 v99, v157, v99
	v_add_f32_e32 v100, v151, v100
	v_add_f32_e32 v101, v156, v101
	v_exp_f32_e32 v78, v78
	v_exp_f32_e32 v79, v79
	v_exp_f32_e32 v80, v80
	v_exp_f32_e32 v81, v81
	v_add_f32_e32 v98, v152, v98
	v_add_f32_e32 v99, v155, v99
	v_add_f32_e32 v100, v153, v100
	v_add_f32_e32 v101, v154, v101
	v_add_f32_e32 v98, v66, v98
	v_add_f32_e32 v99, v67, v99
	v_add_f32_e32 v100, v68, v100
	v_add_f32_e32 v101, v69, v101
	v_add_f32_e32 v98, v70, v98
	v_add_f32_e32 v99, v71, v99
	v_add_f32_e32 v100, v72, v100
	v_add_f32_e32 v101, v73, v101
	v_add_f32_e32 v98, v74, v98
	v_add_f32_e32 v99, v75, v99
	v_add_f32_e32 v100, v76, v100
	v_add_f32_e32 v101, v77, v101
	v_add_f32_e32 v98, v78, v98
	v_add_f32_e32 v99, v79, v99
	v_add_f32_e32 v100, v80, v100
	v_add_f32_e32 v101, v81, v101
	v_add_f32_e32 v98, v98, v99
	v_add_f32_e32 v99, v100, v101
	v_add_f32_e32 v224, v98, v99
	v_mov_b32_e32 v225, v224
	v_cvt_pk_bf16_f32 v146, v146, v161
	v_cvt_pk_bf16_f32 v147, v147, v160
	v_cvt_pk_bf16_f32 v148, v148, v159
	v_cvt_pk_bf16_f32 v149, v149, v158
	v_cvt_pk_bf16_f32 v150, v150, v157
	v_cvt_pk_bf16_f32 v151, v151, v156
	v_cvt_pk_bf16_f32 v152, v152, v155
	v_cvt_pk_bf16_f32 v153, v153, v154
	v_cvt_pk_bf16_f32 v158, v66, v67
	v_cvt_pk_bf16_f32 v159, v68, v69
	v_cvt_pk_bf16_f32 v160, v70, v71
	v_cvt_pk_bf16_f32 v161, v72, v73
	v_cvt_pk_bf16_f32 v154, v74, v75
	v_cvt_pk_bf16_f32 v155, v76, v77
	v_cvt_pk_bf16_f32 v156, v78, v79
	v_cvt_pk_bf16_f32 v157, v80, v81
	s_nop 1
	v_permlane32_swap_b32_e32 v224, v225
	v_cmp_neq_f32_e64 s[6:7], v229, -v226
	s_cmp_eq_u64 s[6:7], 0
	s_cselect_b64 s[6:7], -1, 0
	s_cbranch_scc0 .Lmy_negm_slow_0
	v_mov_b64_e32 v[66:67], v[82:83]
	v_mov_b64_e32 v[68:69], v[84:85]
	v_mov_b64_e32 v[70:71], v[86:87]
	v_mov_b64_e32 v[72:73], v[88:89]
	v_mov_b64_e32 v[74:75], v[90:91]
	v_mov_b64_e32 v[76:77], v[92:93]
	v_mov_b64_e32 v[78:79], v[94:95]
	v_mov_b64_e32 v[80:81], v[96:97]
.Lmy_negm_back_0:
	ds_read_b128 v[82:85], v221 offset:0
	ds_read_b128 v[162:165], v221 offset:0x3000
	ds_read_b128 v[166:169], v220 offset:0
	ds_read_b128 v[170:173], v220 offset:0x3000
	s_waitcnt lgkmcnt(2)
	s_nop 1
	v_mfma_f32_32x32x16_bf16 v[98:113], v[82:85], v[142:145], v[66:81]
	v_mfma_f32_32x32x16_bf16 v[82:97], v[162:165], v[142:145], v[66:81]
	ds_read_b128 v[162:165], v219 offset:0
	ds_read_b128 v[174:177], v219 offset:0x3000
	s_waitcnt lgkmcnt(2)
	v_mfma_f32_32x32x16_bf16 v[98:113], v[166:169], v[138:141], v[98:113]
	ds_read_b128 v[166:169], v218 offset:0
	v_mfma_f32_32x32x16_bf16 v[82:97], v[170:173], v[138:141], v[82:97]
	ds_read_b128 v[170:173], v218 offset:0x3000
	s_waitcnt lgkmcnt(2)
	v_mfma_f32_32x32x16_bf16 v[98:113], v[162:165], v[134:137], v[98:113]
	ds_read_b128 v[162:165], v221 offset:0x80
	v_mfma_f32_32x32x16_bf16 v[82:97], v[174:177], v[134:137], v[82:97]
	ds_read_b128 v[174:177], v221 offset:0x3080
	s_waitcnt lgkmcnt(2)
	v_mfma_f32_32x32x16_bf16 v[98:113], v[166:169], v[130:133], v[98:113]
	ds_read_b128 v[166:169], v220 offset:0x80
	v_mfma_f32_32x32x16_bf16 v[82:97], v[170:173], v[130:133], v[82:97]
	ds_read_b128 v[170:173], v220 offset:0x3080
	s_waitcnt lgkmcnt(2)
	v_mfma_f32_32x32x16_bf16 v[98:113], v[162:165], v[126:129], v[98:113]
	ds_read_b128 v[162:165], v219 offset:0x80
	v_mfma_f32_32x32x16_bf16 v[82:97], v[174:177], v[126:129], v[82:97]
	ds_read_b128 v[174:177], v219 offset:0x3080
	s_waitcnt lgkmcnt(2)
	v_mfma_f32_32x32x16_bf16 v[98:113], v[166:169], v[122:125], v[98:113]
	ds_read_b128 v[166:169], v218 offset:0x80
	v_mfma_f32_32x32x16_bf16 v[82:97], v[170:173], v[122:125], v[82:97]
	ds_read_b128 v[170:173], v218 offset:0x3080
	s_waitcnt lgkmcnt(2)
	v_mfma_f32_32x32x16_bf16 v[98:113], v[162:165], v[118:121], v[98:113]
	ds_read_b128 v[162:165], v221 offset:0x100
	v_mfma_f32_32x32x16_bf16 v[82:97], v[174:177], v[118:121], v[82:97]
	ds_read_b128 v[174:177], v221 offset:0x3100
	ds_read_b128 v[178:181], v199 offset:0
	s_waitcnt lgkmcnt(3)
	v_mfma_f32_32x32x16_bf16 v[98:113], v[166:169], v[114:117], v[98:113]
	ds_read_b128 v[166:169], v220 offset:0x100
	v_mfma_f32_32x32x16_bf16 v[82:97], v[170:173], v[114:117], v[82:97]
	ds_read_b128 v[170:173], v220 offset:0x3100
	ds_read_b128 v[230:233], v199 offset:0x400
	s_waitcnt lgkmcnt(3)
	v_mfma_f32_32x32x16_bf16 v[98:113], v[162:165], v[178:181], v[98:113]
	ds_read_b128 v[162:165], v219 offset:0x100
	v_mfma_f32_32x32x16_bf16 v[82:97], v[174:177], v[178:181], v[82:97]
	ds_read_b128 v[174:177], v219 offset:0x3100
	ds_read_b128 v[178:181], v199 offset:0x800
	s_waitcnt lgkmcnt(3)
	v_mfma_f32_32x32x16_bf16 v[98:113], v[166:169], v[230:233], v[98:113]
	ds_read_b128 v[166:169], v218 offset:0x100
	v_mfma_f32_32x32x16_bf16 v[82:97], v[170:173], v[230:233], v[82:97]
	ds_read_b128 v[170:173], v218 offset:0x3100
	ds_read_b128 v[230:233], v199 offset:0xc00
	s_waitcnt lgkmcnt(3)
	v_mfma_f32_32x32x16_bf16 v[98:113], v[162:165], v[178:181], v[98:113]
	s_waitcnt lgkmcnt(0)
	v_mfma_f32_32x32x16_bf16 v[82:97], v[174:177], v[178:181], v[82:97]
	v_mfma_f32_32x32x16_bf16 v[98:113], v[166:169], v[230:233], v[98:113]
	v_mfma_f32_32x32x16_bf16 v[82:97], v[170:173], v[230:233], v[82:97]
	s_nop 10
	v_max_f32_e32 v162, v98, v102
	v_max_f32_e32 v163, v99, v103
	v_max_f32_e32 v164, v101, v105
	v_max3_f32 v165, v100, v104, v108
	v_max3_f32 v164, v164, v109, v113
	v_max3_f32 v162, v162, v106, v110
	v_max3_f32 v163, v163, v107, v111
	v_max3_f32 v165, v165, v112, v84
	v_max3_f32 v164, v164, v85, v89
	v_max3_f32 v162, v162, v82, v86
	v_max3_f32 v163, v163, v83, v87
	v_max3_f32 v165, v165, v88, v92
	v_max3_f32 v164, v164, v93, v97
	v_max3_f32 v162, v162, v90, v94
	v_max3_f32 v163, v163, v91, v95
	v_max3_f32 v164, v165, v96, v164
	v_max3_f32 v162, v162, v163, v164
	v_cmp_ge_f32_e32 vcc, s48, v162
	s_cmp_eq_u64 vcc, exec
	s_cbranch_scc0 .LBB0_374
	v_mov_b32_e32 v228, v226
	v_mov_b32_e32 v227, 1.0

; __device__ __forceinline__ void qkt12_roll(f32x16& p0, f32x16& p1, const f32x16& negm, int kb, int qa, const bf16x8* qr) {
;   const int a0 = kb ^ (0 << 5); const bf16x8 x0 = lds_rd128<0>(a0), y0 = lds_rd128<12288>(a0);
;   const int a1 = kb ^ (1 << 5); const bf16x8 x1 = lds_rd128<0>(a1), y1 = lds_rd128<12288>(a1);
;   asm volatile("s_waitcnt lgkmcnt(2)" ::: "memory"); SBAR();
;   p0 = __builtin_amdgcn_mfma_f32_32x32x16_bf16(x0, qr[0], negm, 0, 0, 0); p1 = __builtin_amdgcn_mfma_f32_32x32x16_bf16(y0, qr[0], negm, 0, 0, 0);
;   const int a2 = kb ^ (2 << 5); const bf16x8 x2 = lds_rd128<0>(a2), y2 = lds_rd128<12288>(a2);
;   asm volatile("s_waitcnt lgkmcnt(2)" ::: "memory"); SBAR();
;   p0 = __builtin_amdgcn_mfma_f32_32x32x16_bf16(x1, qr[1], p0, 0, 0, 0); p1 = __builtin_amdgcn_mfma_f32_32x32x16_bf16(y1, qr[1], p1, 0, 0, 0);
;   const int a3 = kb ^ (3 << 5); const bf16x8 x3 = lds_rd128<0>(a3), y3 = lds_rd128<12288>(a3);
;   asm volatile("s_waitcnt lgkmcnt(2)" ::: "memory"); SBAR();
;   p0 = __builtin_amdgcn_mfma_f32_32x32x16_bf16(x2, qr[2], p0, 0, 0, 0); p1 = __builtin_amdgcn_mfma_f32_32x32x16_bf16(y2, qr[2], p1, 0, 0, 0);
;   const int a4 = kb ^ (0 << 5); const bf16x8 x4 = lds_rd128<128>(a4), y4 = lds_rd128<12416>(a4);
;   asm volatile("s_waitcnt lgkmcnt(2)" ::: "memory"); SBAR();
;   p0 = __builtin_amdgcn_mfma_f32_32x32x16_bf16(x3, qr[3], p0, 0, 0, 0); p1 = __builtin_amdgcn_mfma_f32_32x32x16_bf16(y3, qr[3], p1, 0, 0, 0);
;   const int a5 = kb ^ (1 << 5); const bf16x8 x5 = lds_rd128<128>(a5), y5 = lds_rd128<12416>(a5);
;   asm volatile("s_waitcnt lgkmcnt(2)" ::: "memory"); SBAR();
;   p0 = __builtin_amdgcn_mfma_f32_32x32x16_bf16(x4, qr[4], p0, 0, 0, 0); p1 = __builtin_amdgcn_mfma_f32_32x32x16_bf16(y4, qr[4], p1, 0, 0, 0);
;   const int a6 = kb ^ (2 << 5); const bf16x8 x6 = lds_rd128<128>(a6), y6 = lds_rd128<12416>(a6);
;   asm volatile("s_waitcnt lgkmcnt(2)" ::: "memory"); SBAR();
;   p0 = __builtin_amdgcn_mfma_f32_32x32x16_bf16(x5, qr[5], p0, 0, 0, 0); p1 = __builtin_amdgcn_mfma_f32_32x32x16_bf16(y5, qr[5], p1, 0, 0, 0);
;   const int a7 = kb ^ (3 << 5); const bf16x8 x7 = lds_rd128<128>(a7), y7 = lds_rd128<12416>(a7);
;   asm volatile("s_waitcnt lgkmcnt(2)" ::: "memory"); SBAR();
;   p0 = __builtin_amdgcn_mfma_f32_32x32x16_bf16(x6, qr[6], p0, 0, 0, 0); p1 = __builtin_amdgcn_mfma_f32_32x32x16_bf16(y6, qr[6], p1, 0, 0, 0);
.LBB0_366:
	v_exp_f32_e32 v146, v98
	v_exp_f32_e32 v153, v99
	v_exp_f32_e32 v147, v100
	v_exp_f32_e32 v152, v101
	v_exp_f32_e32 v148, v102
	v_exp_f32_e32 v151, v103
	v_exp_f32_e32 v149, v104
	v_exp_f32_e32 v150, v105
	v_exp_f32_e32 v103, v106
	v_exp_f32_e32 v105, v107
	v_exp_f32_e32 v101, v108
	v_exp_f32_e32 v104, v109
	v_exp_f32_e32 v99, v110
	v_exp_f32_e32 v102, v111
	v_exp_f32_e32 v98, v112
	v_exp_f32_e32 v100, v113
	v_xor_b32_e32 v106, 0x80000000, v226
	v_exp_f32_e32 v82, v82
	v_exp_f32_e32 v83, v83
	v_exp_f32_e32 v84, v84
	v_exp_f32_e32 v85, v85
	v_cndmask_b32_e64 v229, v106, v229, s[6:7]
	v_exp_f32_e32 v86, v86
	v_exp_f32_e32 v87, v87
	v_exp_f32_e32 v88, v88
	v_exp_f32_e32 v89, v89
	v_add_f32_e32 v106, v148, v146
	v_add_f32_e32 v107, v151, v153
	v_add_f32_e32 v108, v149, v147
	v_add_f32_e32 v109, v150, v152
	v_exp_f32_e32 v90, v90
	v_exp_f32_e32 v91, v91
	v_exp_f32_e32 v92, v92
	v_exp_f32_e32 v93, v93
	v_add_f32_e32 v106, v103, v106
	v_add_f32_e32 v107, v105, v107
	v_add_f32_e32 v108, v101, v108
	v_add_f32_e32 v109, v104, v109
	v_exp_f32_e32 v94, v94
	v_exp_f32_e32 v95, v95
	v_exp_f32_e32 v96, v96
	v_exp_f32_e32 v97, v97
	v_add_f32_e32 v106, v99, v106
	v_add_f32_e32 v107, v102, v107
	v_add_f32_e32 v108, v98, v108
	v_add_f32_e32 v109, v100, v109
	v_add_f32_e32 v106, v82, v106
	v_add_f32_e32 v107, v107, v83
	v_add_f32_e32 v108, v108, v84
	v_add_f32_e32 v109, v109, v85
	v_add_f32_e32 v106, v86, v106
	v_add_f32_e32 v107, v87, v107
	v_add_f32_e32 v108, v88, v108
	v_add_f32_e32 v109, v89, v109
	v_add_f32_e32 v106, v90, v106
	v_add_f32_e32 v107, v91, v107
	v_add_f32_e32 v108, v92, v108
	v_add_f32_e32 v109, v93, v109
	v_add_f32_e32 v106, v94, v106
	v_add_f32_e32 v107, v95, v107
	v_add_f32_e32 v108, v96, v108
	v_add_f32_e32 v109, v97, v109
	v_add_f32_e32 v106, v106, v107
	v_add_f32_e32 v107, v108, v109
	v_add_f32_e32 v230, v106, v107
	s_waitcnt lgkmcnt(0)
	s_barrier
	v_mov_b32_e32 v231, v230
	v_cvt_pk_bf16_f32 v146, v146, v153
	v_cvt_pk_bf16_f32 v147, v147, v152
	v_cvt_pk_bf16_f32 v148, v148, v151
	v_cvt_pk_bf16_f32 v149, v149, v150
	v_cvt_pk_bf16_f32 v150, v103, v105
	v_cvt_pk_bf16_f32 v151, v101, v104
	v_cvt_pk_bf16_f32 v152, v99, v102
	v_cvt_pk_bf16_f32 v153, v98, v100
	v_cvt_pk_bf16_f32 v158, v82, v83
	v_cvt_pk_bf16_f32 v159, v84, v85
	v_cvt_pk_bf16_f32 v160, v86, v87
	v_cvt_pk_bf16_f32 v161, v88, v89
	v_cvt_pk_bf16_f32 v154, v90, v91
	v_cvt_pk_bf16_f32 v155, v92, v93
	v_cvt_pk_bf16_f32 v156, v94, v95
	v_cvt_pk_bf16_f32 v157, v96, v97
	s_nop 1
	v_permlane32_swap_b32_e32 v230, v231
	v_cmp_neq_f32_e64 s[6:7], v229, -v228
	s_cmp_eq_u64 s[6:7], 0
	s_cselect_b64 s[6:7], -1, 0
	s_cbranch_scc0 .Lmy_negm_slow_1
	v_mov_b64_e32 v[82:83], v[66:67]
	v_mov_b64_e32 v[84:85], v[68:69]
	v_mov_b64_e32 v[86:87], v[70:71]
	v_mov_b64_e32 v[88:89], v[72:73]
	v_mov_b64_e32 v[90:91], v[74:75]
	v_mov_b64_e32 v[92:93], v[76:77]
	v_mov_b64_e32 v[94:95], v[78:79]
	v_mov_b64_e32 v[96:97], v[80:81]
.Lmy_negm_back_1:
	ds_read_b128 v[66:69], v209 offset:0
	ds_read_b128 v[162:165], v209 offset:0x3000
	ds_read_b128 v[166:169], v215 offset:0
	ds_read_b128 v[170:173], v215 offset:0x3000
	s_waitcnt lgkmcnt(2)
	s_nop 1
	v_mfma_f32_32x32x16_bf16 v[98:113], v[66:69], v[142:145], v[82:97]
	v_mfma_f32_32x32x16_bf16 v[66:81], v[162:165], v[142:145], v[82:97]
	ds_read_b128 v[162:165], v216 offset:0
	ds_read_b128 v[174:177], v216 offset:0x3000
	s_waitcnt lgkmcnt(2)
	v_mfma_f32_32x32x16_bf16 v[98:113], v[166:169], v[138:141], v[98:113]
	ds_read_b128 v[166:169], v217 offset:0
	v_mfma_f32_32x32x16_bf16 v[66:81], v[170:173], v[138:141], v[66:81]
	ds_read_b128 v[170:173], v217 offset:0x3000
	s_waitcnt lgkmcnt(2)
	v_mfma_f32_32x32x16_bf16 v[98:113], v[162:165], v[134:137], v[98:113]
	ds_read_b128 v[162:165], v209 offset:0x80
	v_mfma_f32_32x32x16_bf16 v[66:81], v[174:177], v[134:137], v[66:81]
	ds_read_b128 v[174:177], v209 offset:0x3080
	s_waitcnt lgkmcnt(2)
	v_mfma_f32_32x32x16_bf16 v[98:113], v[166:169], v[130:133], v[98:113]
	ds_read_b128 v[166:169], v215 offset:0x80
	v_mfma_f32_32x32x16_bf16 v[66:81], v[170:173], v[130:133], v[66:81]
	ds_read_b128 v[170:173], v215 offset:0x3080
	s_waitcnt lgkmcnt(2)
	v_mfma_f32_32x32x16_bf16 v[98:113], v[162:165], v[126:129], v[98:113]
	ds_read_b128 v[162:165], v216 offset:0x80
	v_mfma_f32_32x32x16_bf16 v[66:81], v[174:177], v[126:129], v[66:81]
	ds_read_b128 v[174:177], v216 offset:0x3080
	s_waitcnt lgkmcnt(2)
	v_mfma_f32_32x32x16_bf16 v[98:113], v[166:169], v[122:125], v[98:113]
	ds_read_b128 v[166:169], v217 offset:0x80
	v_mfma_f32_32x32x16_bf16 v[66:81], v[170:173], v[122:125], v[66:81]
	ds_read_b128 v[170:173], v217 offset:0x3080
	s_waitcnt lgkmcnt(2)
	v_mfma_f32_32x32x16_bf16 v[98:113], v[162:165], v[118:121], v[98:113]
	ds_read_b128 v[162:165], v209 offset:0x100
	v_mfma_f32_32x32x16_bf16 v[66:81], v[174:177], v[118:121], v[66:81]
	ds_read_b128 v[174:177], v209 offset:0x3100
	ds_read_b128 v[178:181], v199 offset:0
	s_waitcnt lgkmcnt(3)
	v_mfma_f32_32x32x16_bf16 v[98:113], v[166:169], v[114:117], v[98:113]
	ds_read_b128 v[166:169], v215 offset:0x100
	v_mfma_f32_32x32x16_bf16 v[66:81], v[170:173], v[114:117], v[66:81]
	ds_read_b128 v[170:173], v215 offset:0x3100
	ds_read_b128 v[232:235], v199 offset:0x400
	s_waitcnt lgkmcnt(3)
	v_mfma_f32_32x32x16_bf16 v[98:113], v[162:165], v[178:181], v[98:113]
	ds_read_b128 v[162:165], v216 offset:0x100
	v_mfma_f32_32x32x16_bf16 v[66:81], v[174:177], v[178:181], v[66:81]
	ds_read_b128 v[174:177], v216 offset:0x3100
	ds_read_b128 v[178:181], v199 offset:0x800
	s_waitcnt lgkmcnt(3)
	v_mfma_f32_32x32x16_bf16 v[98:113], v[166:169], v[232:235], v[98:113]
	ds_read_b128 v[166:169], v217 offset:0x100
	v_mfma_f32_32x32x16_bf16 v[66:81], v[170:173], v[232:235], v[66:81]
	ds_read_b128 v[170:173], v217 offset:0x3100
	ds_read_b128 v[232:235], v199 offset:0xc00
	s_waitcnt lgkmcnt(3)
	v_mfma_f32_32x32x16_bf16 v[98:113], v[162:165], v[178:181], v[98:113]
	s_waitcnt lgkmcnt(0)
	v_mfma_f32_32x32x16_bf16 v[66:81], v[174:177], v[178:181], v[66:81]
	v_mfma_f32_32x32x16_bf16 v[98:113], v[166:169], v[232:235], v[98:113]
	v_mfma_f32_32x32x16_bf16 v[66:81], v[170:173], v[232:235], v[66:81]
	s_nop 10
	v_max_f32_e32 v162, v98, v102
	v_max_f32_e32 v163, v99, v103
	v_max_f32_e32 v164, v101, v105
	v_max3_f32 v165, v100, v104, v108
	v_max3_f32 v164, v164, v109, v113
	v_max3_f32 v162, v162, v106, v110
	v_max3_f32 v163, v163, v107, v111
	v_max3_f32 v165, v165, v112, v68
	v_max3_f32 v164, v164, v69, v73
	v_max3_f32 v162, v162, v66, v70
	v_max3_f32 v163, v163, v67, v71
	v_max3_f32 v165, v165, v72, v76
	v_max3_f32 v164, v164, v77, v81
	v_max3_f32 v162, v162, v74, v78
	v_max3_f32 v163, v163, v75, v79
	v_max3_f32 v164, v165, v80, v164
	v_max3_f32 v162, v162, v163, v164
	v_cmp_ge_f32_e32 vcc, s48, v162
	s_cmp_eq_u64 vcc, exec
	v_mov_b32_e32 v223, 1.0
	s_cbranch_scc0 .LBB0_375
	v_mov_b32_e32 v226, v228

.Lmy_negm_slow_0:
	v_cndmask_b32_e64 v81, -v226, v97, s[6:7]
	v_cndmask_b32_e64 v80, -v226, v96, s[6:7]
	v_cndmask_b32_e64 v79, -v226, v95, s[6:7]
	v_cndmask_b32_e64 v78, -v226, v94, s[6:7]
	v_cndmask_b32_e64 v77, -v226, v93, s[6:7]
	v_cndmask_b32_e64 v76, -v226, v92, s[6:7]
	v_cndmask_b32_e64 v75, -v226, v91, s[6:7]
	v_cndmask_b32_e64 v74, -v226, v90, s[6:7]
	v_cndmask_b32_e64 v73, -v226, v89, s[6:7]
	v_cndmask_b32_e64 v72, -v226, v88, s[6:7]
	v_cndmask_b32_e64 v71, -v226, v87, s[6:7]
	v_cndmask_b32_e64 v70, -v226, v86, s[6:7]
	v_cndmask_b32_e64 v69, -v226, v85, s[6:7]
	v_cndmask_b32_e64 v68, -v226, v84, s[6:7]
	v_cndmask_b32_e64 v67, -v226, v83, s[6:7]
	v_cndmask_b32_e64 v66, -v226, v82, s[6:7]
	s_branch .Lmy_negm_back_0
.Lmy_negm_slow_1:
	v_cndmask_b32_e64 v97, -v228, v81, s[6:7]
	v_cndmask_b32_e64 v96, -v228, v80, s[6:7]
	v_cndmask_b32_e64 v95, -v228, v79, s[6:7]
	v_cndmask_b32_e64 v94, -v228, v78, s[6:7]
	v_cndmask_b32_e64 v93, -v228, v77, s[6:7]
	v_cndmask_b32_e64 v92, -v228, v76, s[6:7]
	v_cndmask_b32_e64 v91, -v228, v75, s[6:7]
	v_cndmask_b32_e64 v90, -v228, v74, s[6:7]
	v_cndmask_b32_e64 v89, -v228, v73, s[6:7]
	v_cndmask_b32_e64 v88, -v228, v72, s[6:7]
	v_cndmask_b32_e64 v87, -v228, v71, s[6:7]
	v_cndmask_b32_e64 v86, -v228, v70, s[6:7]
	v_cndmask_b32_e64 v85, -v228, v69, s[6:7]
	v_cndmask_b32_e64 v84, -v228, v68, s[6:7]
	v_cndmask_b32_e64 v83, -v228, v67, s[6:7]
	v_cndmask_b32_e64 v82, -v228, v66, s[6:7]
	s_branch .Lmy_negm_back_1

; __device__ __forceinline__ void qkt12_roll(f32x16& p0, f32x16& p1, const f32x16& negm, int kb, int qa, const bf16x8* qr) {
;   const int a0 = kb ^ (0 << 5); const bf16x8 x0 = lds_rd128<0>(a0), y0 = lds_rd128<12288>(a0);
;   const int a1 = kb ^ (1 << 5); const bf16x8 x1 = lds_rd128<0>(a1), y1 = lds_rd128<12288>(a1);
;   asm volatile("s_waitcnt lgkmcnt(2)" ::: "memory"); SBAR();
;   p0 = __builtin_amdgcn_mfma_f32_32x32x16_bf16(x0, qr[0], negm, 0, 0, 0); p1 = __builtin_amdgcn_mfma_f32_32x32x16_bf16(y0, qr[0], negm, 0, 0, 0);
;   const int a2 = kb ^ (2 << 5); const bf16x8 x2 = lds_rd128<0>(a2), y2 = lds_rd128<12288>(a2);
;   asm volatile("s_waitcnt lgkmcnt(2)" ::: "memory"); SBAR();
;   p0 = __builtin_amdgcn_mfma_f32_32x32x16_bf16(x1, qr[1], p0, 0, 0, 0); p1 = __builtin_amdgcn_mfma_f32_32x32x16_bf16(y1, qr[1], p1, 0, 0, 0);
;   const int a3 = kb ^ (3 << 5); const bf16x8 x3 = lds_rd128<0>(a3), y3 = lds_rd128<12288>(a3);
;   asm volatile("s_waitcnt lgkmcnt(2)" ::: "memory"); SBAR();
;   p0 = __builtin_amdgcn_mfma_f32_32x32x16_bf16(x2, qr[2], p0, 0, 0, 0); p1 = __builtin_amdgcn_mfma_f32_32x32x16_bf16(y2, qr[2], p1, 0, 0, 0);
;   const int a4 = kb ^ (0 << 5); const bf16x8 x4 = lds_rd128<128>(a4), y4 = lds_rd128<12416>(a4);
;   asm volatile("s_waitcnt lgkmcnt(2)" ::: "memory"); SBAR();
;   p0 = __builtin_amdgcn_mfma_f32_32x32x16_bf16(x3, qr[3], p0, 0, 0, 0); p1 = __builtin_amdgcn_mfma_f32_32x32x16_bf16(y3, qr[3], p1, 0, 0, 0);
;   const int a5 = kb ^ (1 << 5); const bf16x8 x5 = lds_rd128<128>(a5), y5 = lds_rd128<12416>(a5);
;   asm volatile("s_waitcnt lgkmcnt(2)" ::: "memory"); SBAR();
;   p0 = __builtin_amdgcn_mfma_f32_32x32x16_bf16(x4, qr[4], p0, 0, 0, 0); p1 = __builtin_amdgcn_mfma_f32_32x32x16_bf16(y4, qr[4], p1, 0, 0, 0);
;   const int a6 = kb ^ (2 << 5); const bf16x8 x6 = lds_rd128<128>(a6), y6 = lds_rd128<12416>(a6);
;   asm volatile("s_waitcnt lgkmcnt(2)" ::: "memory"); SBAR();
;   p0 = __builtin_amdgcn_mfma_f32_32x32x16_bf16(x5, qr[5], p0, 0, 0, 0); p1 = __builtin_amdgcn_mfma_f32_32x32x16_bf16(y5, qr[5], p1, 0, 0, 0);
;   const int a7 = kb ^ (3 << 5); const bf16x8 x7 = lds_rd128<128>(a7), y7 = lds_rd128<12416>(a7);
;   asm volatile("s_waitcnt lgkmcnt(2)" ::: "memory"); SBAR();
;   p0 = __builtin_amdgcn_mfma_f32_32x32x16_bf16(x6, qr[6], p0, 0, 0, 0); p1 = __builtin_amdgcn_mfma_f32_32x32x16_bf16(y6, qr[6], p1, 0, 0, 0);
.LBB0_386:
	v_cmp_neq_f32_e64 s[6:7], v228, -v225
	s_cmp_eq_u64 s[6:7], 0
	s_cselect_b64 s[6:7], -1, 0
	s_cbranch_scc1 .Lmy_negm_skip_0
	v_cndmask_b32_e64 v113, -v225, v113, s[6:7]
	v_cndmask_b32_e64 v112, -v225, v112, s[6:7]
	v_cndmask_b32_e64 v111, -v225, v111, s[6:7]
	v_cndmask_b32_e64 v110, -v225, v110, s[6:7]
	v_cndmask_b32_e64 v109, -v225, v109, s[6:7]
	v_cndmask_b32_e64 v108, -v225, v108, s[6:7]
	v_cndmask_b32_e64 v107, -v225, v107, s[6:7]
	v_cndmask_b32_e64 v106, -v225, v106, s[6:7]
	v_cndmask_b32_e64 v105, -v225, v105, s[6:7]
	v_cndmask_b32_e64 v104, -v225, v104, s[6:7]
	v_cndmask_b32_e64 v103, -v225, v103, s[6:7]
	v_cndmask_b32_e64 v102, -v225, v102, s[6:7]
	v_cndmask_b32_e64 v101, -v225, v101, s[6:7]
	v_cndmask_b32_e64 v100, -v225, v100, s[6:7]
	v_cndmask_b32_e64 v99, -v225, v99, s[6:7]
	v_cndmask_b32_e64 v98, -v225, v98, s[6:7]
.Lmy_negm_skip_0:
	ds_read_b128 v[82:85], v221 offset:0
	ds_read_b128 v[230:233], v221 offset:0x3000
	ds_read_b128 v[234:237], v220 offset:0
	ds_read_b128 v[238:241], v220 offset:0x3000
	s_waitcnt lgkmcnt(2)
	s_nop 1
	v_mfma_f32_32x32x16_bf16 v[114:129], v[82:85], v[158:161], v[98:113]
	v_mfma_f32_32x32x16_bf16 v[82:97], v[230:233], v[158:161], v[98:113]
	ds_read_b128 v[230:233], v219 offset:0
	ds_read_b128 v[242:245], v219 offset:0x3000
	s_waitcnt lgkmcnt(2)
	v_mfma_f32_32x32x16_bf16 v[114:129], v[234:237], v[154:157], v[114:129]
	ds_read_b128 v[234:237], v218 offset:0
	v_mfma_f32_32x32x16_bf16 v[82:97], v[238:241], v[154:157], v[82:97]
	ds_read_b128 v[238:241], v218 offset:0x3000
	s_waitcnt lgkmcnt(2)
	v_mfma_f32_32x32x16_bf16 v[114:129], v[230:233], v[150:153], v[114:129]
	ds_read_b128 v[230:233], v221 offset:0x80
	v_mfma_f32_32x32x16_bf16 v[82:97], v[242:245], v[150:153], v[82:97]
	ds_read_b128 v[242:245], v221 offset:0x3080
	s_waitcnt lgkmcnt(2)
	v_mfma_f32_32x32x16_bf16 v[114:129], v[234:237], v[146:149], v[114:129]
	ds_read_b128 v[234:237], v220 offset:0x80
	v_mfma_f32_32x32x16_bf16 v[82:97], v[238:241], v[146:149], v[82:97]
	ds_read_b128 v[238:241], v220 offset:0x3080
	s_waitcnt lgkmcnt(2)
	v_mfma_f32_32x32x16_bf16 v[114:129], v[230:233], v[142:145], v[114:129]
	ds_read_b128 v[230:233], v219 offset:0x80
	v_mfma_f32_32x32x16_bf16 v[82:97], v[242:245], v[142:145], v[82:97]
	ds_read_b128 v[242:245], v219 offset:0x3080
	s_waitcnt lgkmcnt(2)
	v_mfma_f32_32x32x16_bf16 v[114:129], v[234:237], v[138:141], v[114:129]
	ds_read_b128 v[234:237], v218 offset:0x80
	v_mfma_f32_32x32x16_bf16 v[82:97], v[238:241], v[138:141], v[82:97]
	ds_read_b128 v[238:241], v218 offset:0x3080
	s_waitcnt lgkmcnt(2)
	v_mfma_f32_32x32x16_bf16 v[114:129], v[230:233], v[134:137], v[114:129]
	ds_read_b128 v[230:233], v221 offset:0x100
	v_mfma_f32_32x32x16_bf16 v[82:97], v[242:245], v[134:137], v[82:97]
	ds_read_b128 v[242:245], v221 offset:0x3100
	ds_read_b128 v[246:249], v199 offset:0
	s_waitcnt lgkmcnt(3)
	v_mfma_f32_32x32x16_bf16 v[114:129], v[234:237], v[130:133], v[114:129]
	ds_read_b128 v[234:237], v220 offset:0x100
	v_mfma_f32_32x32x16_bf16 v[82:97], v[238:241], v[130:133], v[82:97]
	ds_read_b128 v[238:241], v220 offset:0x3100
	ds_read_b128 v[250:253], v199 offset:0x400
	s_waitcnt lgkmcnt(3)
	v_mfma_f32_32x32x16_bf16 v[114:129], v[230:233], v[246:249], v[114:129]
	ds_read_b128 v[230:233], v219 offset:0x100
	v_mfma_f32_32x32x16_bf16 v[82:97], v[242:245], v[246:249], v[82:97]
	ds_read_b128 v[242:245], v219 offset:0x3100
	ds_read_b128 v[246:249], v199 offset:0x800
	s_waitcnt lgkmcnt(3)
	v_mfma_f32_32x32x16_bf16 v[114:129], v[234:237], v[250:253], v[114:129]
	ds_read_b128 v[234:237], v218 offset:0x100
	v_mfma_f32_32x32x16_bf16 v[82:97], v[238:241], v[250:253], v[82:97]
	ds_read_b128 v[238:241], v218 offset:0x3100
	ds_read_b128 v[250:253], v199 offset:0xc00
	s_waitcnt lgkmcnt(3)
	v_mfma_f32_32x32x16_bf16 v[114:129], v[230:233], v[246:249], v[114:129]
	s_waitcnt lgkmcnt(0)
; __device__ __forceinline__ void pv_d0(f32x16* o, int vb, bf16x8 pa0, bf16x8 pa1, bf16x8 pa2, bf16x8 pa3) {
;     ...
;   const s16x4 l0 = tr_read<v_rd_off(0, 0, 0)>(vb), h0 = tr_read<v_rd_off(0, 0, 1)>(vb);
;   const s16x4 l1 = tr_read<v_rd_off(0, 1, 0)>(vb), h1 = tr_read<v_rd_off(0, 1, 1)>(vb);
;   const s16x4 l2 = tr_read<v_rd_off(0, 2, 0)>(vb), h2 = tr_read<v_rd_off(0, 2, 1)>(vb);
;   const s16x4 l3 = tr_read<v_rd_off(0, 3, 0)>(vb), h3 = tr_read<v_rd_off(0, 3, 1)>(vb);
;   const s16x4 l4 = tr_read<v_rd_off(1, 0, 0)>(vb), h4 = tr_read<v_rd_off(1, 0, 1)>(vb);
;   asm volatile("s_waitcnt lgkmcnt(8)" ::: "memory"); SBAR();
;   o[0] = __builtin_amdgcn_mfma_f32_32x32x16_bf16(pa0, PK(l0, h0), o[0], 0, 0, 0);
;   const s16x4 l5 = tr_read<v_rd_off(1, 1, 0)>(vb), h5 = tr_read<v_rd_off(1, 1, 1)>(vb);
;   asm volatile("s_waitcnt lgkmcnt(8)" ::: "memory"); SBAR();
;   o[0] = __builtin_amdgcn_mfma_f32_32x32x16_bf16(pa1, PK(l1, h1), o[0], 0, 0, 0);
;   const s16x4 l6 = tr_read<v_rd_off(1, 2, 0)>(vb), h6 = tr_read<v_rd_off(1, 2, 1)>(vb);
;   asm volatile("s_waitcnt lgkmcnt(8)" ::: "memory"); SBAR();
;   o[0] = __builtin_amdgcn_mfma_f32_32x32x16_bf16(pa2, PK(l2, h2), o[0], 0, 0, 0);
;   const s16x4 l7 = tr_read<v_rd_off(1, 3, 0)>(vb), h7 = tr_read<v_rd_off(1, 3, 1)>(vb);
;   asm volatile("s_waitcnt lgkmcnt(8)" ::: "memory"); SBAR();
;   o[0] = __builtin_amdgcn_mfma_f32_32x32x16_bf16(pa3, PK(l3, h3), o[0], 0, 0, 0);
;   const s16x4 l8 = tr_read<v_rd_off(2, 0, 0)>(vb), h8 = tr_read<v_rd_off(2, 0, 1)>(vb);
;   asm volatile("s_waitcnt lgkmcnt(8)" ::: "memory"); SBAR();
;   o[1] = __builtin_amdgcn_mfma_f32_32x32x16_bf16(pa0, PK(l4, h4), o[1], 0, 0, 0);
;   const s16x4 l9 = tr_read<v_rd_off(2, 1, 0)>(vb), h9 = tr_read<v_rd_off(2, 1, 1)>(vb);
;   asm volatile("s_waitcnt lgkmcnt(8)" ::: "memory"); SBAR();
;   o[1] = __builtin_amdgcn_mfma_f32_32x32x16_bf16(pa1, PK(l5, h5), o[1], 0, 0, 0);
;   const s16x4 l10 = tr_read<v_rd_off(2, 2, 0)>(vb), h10 = tr_read<v_rd_off(2, 2, 1)>(vb);
;   asm volatile("s_waitcnt lgkmcnt(8)" ::: "memory"); SBAR();
;   o[1] = __builtin_amdgcn_mfma_f32_32x32x16_bf16(pa2, PK(l6, h6), o[1], 0, 0, 0);
;   const s16x4 l11 = tr_read<v_rd_off(2, 3, 0)>(vb), h11 = tr_read<v_rd_off(2, 3, 1)>(vb);
;   asm volatile("s_waitcnt lgkmcnt(8)" ::: "memory"); SBAR();
;   o[1] = __builtin_amdgcn_mfma_f32_32x32x16_bf16(pa3, PK(l7, h7), o[1], 0, 0, 0);
	v_mfma_f32_32x32x16_bf16 v[82:97], v[242:245], v[246:249], v[82:97]
	v_mfma_f32_32x32x16_bf16 v[114:129], v[234:237], v[250:253], v[114:129]
	v_mfma_f32_32x32x16_bf16 v[82:97], v[238:241], v[250:253], v[82:97]
	v_exp_f32_e32 v66, v66
	v_exp_f32_e32 v67, v67
	v_exp_f32_e32 v68, v68
	v_exp_f32_e32 v69, v69
	v_exp_f32_e32 v70, v70
	v_exp_f32_e32 v71, v71
	v_exp_f32_e32 v72, v72
	v_exp_f32_e32 v73, v73
	v_add_f32_e32 v166, v168, v176
	v_add_f32_e32 v179, v175, v178
	v_add_f32_e32 v180, v169, v167
	v_add_f32_e32 v181, v174, v177
	v_exp_f32_e32 v74, v74
	v_exp_f32_e32 v75, v75
	v_exp_f32_e32 v76, v76
	v_exp_f32_e32 v77, v77
	v_add_f32_e32 v166, v170, v166
	v_add_f32_e32 v179, v173, v179
	v_add_f32_e32 v180, v165, v180
	v_add_f32_e32 v181, v171, v181
	v_exp_f32_e32 v78, v78
	v_exp_f32_e32 v79, v79
	v_exp_f32_e32 v80, v80
	v_exp_f32_e32 v81, v81
	v_add_f32_e32 v166, v163, v166
	v_add_f32_e32 v179, v172, v179
	v_add_f32_e32 v180, v162, v180
	v_add_f32_e32 v181, v164, v181
	v_add_f32_e32 v166, v66, v166
	v_add_f32_e32 v179, v67, v179
	v_add_f32_e32 v180, v68, v180
	v_add_f32_e32 v181, v69, v181
	v_add_f32_e32 v166, v70, v166
	v_add_f32_e32 v179, v71, v179
	v_add_f32_e32 v180, v72, v180
	v_add_f32_e32 v181, v73, v181
	v_add_f32_e32 v166, v74, v166
	v_add_f32_e32 v179, v75, v179
	v_add_f32_e32 v180, v76, v180
	v_add_f32_e32 v181, v77, v181
	v_add_f32_e32 v166, v78, v166
	v_add_f32_e32 v179, v79, v179
	v_add_f32_e32 v180, v80, v180
	v_add_f32_e32 v181, v81, v181
	v_add_f32_e32 v166, v166, v179
	v_add_f32_e32 v179, v180, v181
	v_add_f32_e32 v223, v166, v179
	v_mov_b32_e32 v224, v223
	v_cvt_pk_bf16_f32 v166, v176, v178
	v_cvt_pk_bf16_f32 v167, v167, v177
	v_cvt_pk_bf16_f32 v168, v168, v175
	s_nop 1
	v_permlane32_swap_b32_e32 v223, v224
	v_cvt_pk_bf16_f32 v169, v169, v174
	v_cvt_pk_bf16_f32 v170, v170, v173
	v_cvt_pk_bf16_f32 v171, v165, v171
	v_cvt_pk_bf16_f32 v172, v163, v172
	v_cvt_pk_bf16_f32 v173, v162, v164
	v_cvt_pk_bf16_f32 v174, v66, v67
	v_cvt_pk_bf16_f32 v175, v68, v69
	v_cvt_pk_bf16_f32 v176, v70, v71
	v_cvt_pk_bf16_f32 v177, v72, v73
	v_cvt_pk_bf16_f32 v178, v74, v75
	v_cvt_pk_bf16_f32 v179, v76, v77
	v_cvt_pk_bf16_f32 v180, v78, v79
	v_cvt_pk_bf16_f32 v181, v80, v81
	v_lshl_add_u64 v[190:191], s[42:43], 0, v[188:189]
	v_add_co_u32_e32 v70, vcc, s49, v190
	v_lshl_add_u64 v[196:197], s[42:43], 0, v[186:187]
	s_nop 0
	v_addc_co_u32_e32 v71, vcc, 0, v191, vcc
	v_add_co_u32_e32 v74, vcc, s28, v190
	s_nop 1
	v_addc_co_u32_e32 v75, vcc, 0, v191, vcc
	global_load_dwordx4 v[66:69], v[70:71], off offset:256
	s_nop 0
	global_load_dwordx4 v[70:73], v[70:71], off
	s_nop 0
	global_load_dwordx4 v[78:81], v[74:75], off offset:256
	s_nop 0
	global_load_dwordx4 v[74:77], v[74:75], off
	v_add_co_u32_e32 v162, vcc, s68, v196
	s_nop 1
	v_addc_co_u32_e32 v163, vcc, 0, v197, vcc
	global_load_dwordx4 v[162:165], v[162:163], off
	ds_read_b64_tr_b16 v[230:231], v201 offset:0
	ds_read_b64_tr_b16 v[232:233], v201 offset:0x800
	ds_read_b64_tr_b16 v[234:235], v201 offset:0x1000
	ds_read_b64_tr_b16 v[236:237], v201 offset:0x1800
	ds_read_b64_tr_b16 v[238:239], v201 offset:0x2000
	ds_read_b64_tr_b16 v[240:241], v201 offset:0x2800
	ds_read_b64_tr_b16 v[242:243], v201 offset:0x3000
	ds_read_b64_tr_b16 v[244:245], v201 offset:0x3800
	ds_read_b64_tr_b16 v[246:247], v201 offset:0x200
	ds_read_b64_tr_b16 v[248:249], v201 offset:0xa00
	s_waitcnt lgkmcnt(8)
	s_nop 0
	v_mfma_f32_32x32x16_bf16 v[2:17], v[166:169], v[230:233], v[2:17]
	ds_read_b64_tr_b16 v[230:231], v201 offset:0x1200
	ds_read_b64_tr_b16 v[232:233], v201 offset:0x1a00
	s_waitcnt lgkmcnt(8)
	v_mfma_f32_32x32x16_bf16 v[2:17], v[170:173], v[234:237], v[2:17]
	ds_read_b64_tr_b16 v[234:235], v201 offset:0x2200
	ds_read_b64_tr_b16 v[236:237], v201 offset:0x2a00
	s_waitcnt lgkmcnt(8)
	v_mfma_f32_32x32x16_bf16 v[2:17], v[174:177], v[238:241], v[2:17]
	ds_read_b64_tr_b16 v[238:239], v201 offset:0x3200
	ds_read_b64_tr_b16 v[240:241], v201 offset:0x3a00
	s_waitcnt lgkmcnt(8)
	v_mfma_f32_32x32x16_bf16 v[2:17], v[178:181], v[242:245], v[2:17]
	ds_read_b64_tr_b16 v[242:243], v201 offset:0x400
	ds_read_b64_tr_b16 v[244:245], v201 offset:0xc00
	s_waitcnt lgkmcnt(8)
	v_mfma_f32_32x32x16_bf16 v[50:65], v[166:169], v[246:249], v[50:65]
	ds_read_b64_tr_b16 v[246:247], v201 offset:0x1400
	ds_read_b64_tr_b16 v[248:249], v201 offset:0x1c00
	s_waitcnt lgkmcnt(8)
	v_mfma_f32_32x32x16_bf16 v[50:65], v[170:173], v[230:233], v[50:65]
	ds_read_b64_tr_b16 v[230:231], v201 offset:0x2400
	ds_read_b64_tr_b16 v[232:233], v201 offset:0x2c00
	s_waitcnt lgkmcnt(8)
	v_mfma_f32_32x32x16_bf16 v[50:65], v[174:177], v[234:237], v[50:65]
	ds_read_b64_tr_b16 v[234:235], v201 offset:0x3400
	ds_read_b64_tr_b16 v[236:237], v201 offset:0x3c00
	s_waitcnt lgkmcnt(8)
	v_mfma_f32_32x32x16_bf16 v[50:65], v[178:181], v[238:241], v[50:65]
	ds_read_b64_tr_b16 v[238:239], v201 offset:0x600
	ds_read_b64_tr_b16 v[240:241], v201 offset:0xe00
	s_waitcnt lgkmcnt(8)
	v_mfma_f32_32x32x16_bf16 v[34:49], v[166:169], v[242:245], v[34:49]
	ds_read_b64_tr_b16 v[242:243], v201 offset:0x1600
	ds_read_b64_tr_b16 v[244:245], v201 offset:0x1e00
	s_waitcnt lgkmcnt(8)
	v_mfma_f32_32x32x16_bf16 v[34:49], v[170:173], v[246:249], v[34:49]
	ds_read_b64_tr_b16 v[246:247], v201 offset:0x2600
	ds_read_b64_tr_b16 v[248:249], v201 offset:0x2e00
	s_waitcnt lgkmcnt(8)
	v_mfma_f32_32x32x16_bf16 v[34:49], v[174:177], v[230:233], v[34:49]
	ds_read_b64_tr_b16 v[230:231], v201 offset:0x3600
	ds_read_b64_tr_b16 v[232:233], v201 offset:0x3e00
	s_waitcnt lgkmcnt(8)
	v_mfma_f32_32x32x16_bf16 v[34:49], v[178:181], v[234:237], v[34:49]
	s_waitcnt lgkmcnt(6)
	v_mfma_f32_32x32x16_bf16 v[18:33], v[166:169], v[238:241], v[18:33]
	s_waitcnt lgkmcnt(4)
	v_mfma_f32_32x32x16_bf16 v[18:33], v[170:173], v[242:245], v[18:33]
	s_waitcnt lgkmcnt(2)
	v_mfma_f32_32x32x16_bf16 v[18:33], v[174:177], v[246:249], v[18:33]
	s_waitcnt lgkmcnt(0)
	v_max_f32_e32 v166, v114, v118
	v_max_f32_e32 v167, v115, v119
	v_max_f32_e32 v168, v117, v121
	v_max3_f32 v169, v116, v120, v124
	v_max3_f32 v168, v168, v125, v129
	v_max3_f32 v166, v166, v122, v126
	v_max3_f32 v167, v167, v123, v127
	v_max3_f32 v169, v169, v128, v84
	v_max3_f32 v168, v168, v85, v89
	v_max3_f32 v166, v166, v82, v86
	v_max3_f32 v167, v167, v83, v87
	v_max3_f32 v169, v169, v88, v92
	v_max3_f32 v168, v168, v93, v97
	v_mfma_f32_32x32x16_bf16 v[18:33], v[178:181], v[230:233], v[18:33]
	v_max3_f32 v166, v166, v90, v94
	v_max3_f32 v167, v167, v91, v95
	v_max3_f32 v168, v169, v96, v168
	v_max3_f32 v166, v166, v167, v168
	v_cmp_ge_f32_e32 vcc, s48, v166
	s_cmp_eq_u64 vcc, exec
	s_cbranch_scc0 .LBB0_400
	v_mov_b32_e32 v227, v225
	v_mov_b32_e32 v226, 1.0

; __device__ __forceinline__ void qkt12_roll(f32x16& p0, f32x16& p1, const f32x16& negm, int kb, int qa, const bf16x8* qr) {
;   const int a0 = kb ^ (0 << 5); const bf16x8 x0 = lds_rd128<0>(a0), y0 = lds_rd128<12288>(a0);
;   const int a1 = kb ^ (1 << 5); const bf16x8 x1 = lds_rd128<0>(a1), y1 = lds_rd128<12288>(a1);
;   asm volatile("s_waitcnt lgkmcnt(2)" ::: "memory"); SBAR();
;   p0 = __builtin_amdgcn_mfma_f32_32x32x16_bf16(x0, qr[0], negm, 0, 0, 0); p1 = __builtin_amdgcn_mfma_f32_32x32x16_bf16(y0, qr[0], negm, 0, 0, 0);
;   const int a2 = kb ^ (2 << 5); const bf16x8 x2 = lds_rd128<0>(a2), y2 = lds_rd128<12288>(a2);
;   asm volatile("s_waitcnt lgkmcnt(2)" ::: "memory"); SBAR();
;   p0 = __builtin_amdgcn_mfma_f32_32x32x16_bf16(x1, qr[1], p0, 0, 0, 0); p1 = __builtin_amdgcn_mfma_f32_32x32x16_bf16(y1, qr[1], p1, 0, 0, 0);
;   const int a3 = kb ^ (3 << 5); const bf16x8 x3 = lds_rd128<0>(a3), y3 = lds_rd128<12288>(a3);
;   asm volatile("s_waitcnt lgkmcnt(2)" ::: "memory"); SBAR();
;   p0 = __builtin_amdgcn_mfma_f32_32x32x16_bf16(x2, qr[2], p0, 0, 0, 0); p1 = __builtin_amdgcn_mfma_f32_32x32x16_bf16(y2, qr[2], p1, 0, 0, 0);
;   const int a4 = kb ^ (0 << 5); const bf16x8 x4 = lds_rd128<128>(a4), y4 = lds_rd128<12416>(a4);
;   asm volatile("s_waitcnt lgkmcnt(2)" ::: "memory"); SBAR();
;   p0 = __builtin_amdgcn_mfma_f32_32x32x16_bf16(x3, qr[3], p0, 0, 0, 0); p1 = __builtin_amdgcn_mfma_f32_32x32x16_bf16(y3, qr[3], p1, 0, 0, 0);
;   const int a5 = kb ^ (1 << 5); const bf16x8 x5 = lds_rd128<128>(a5), y5 = lds_rd128<12416>(a5);
;   asm volatile("s_waitcnt lgkmcnt(2)" ::: "memory"); SBAR();
;   p0 = __builtin_amdgcn_mfma_f32_32x32x16_bf16(x4, qr[4], p0, 0, 0, 0); p1 = __builtin_amdgcn_mfma_f32_32x32x16_bf16(y4, qr[4], p1, 0, 0, 0);
;   const int a6 = kb ^ (2 << 5); const bf16x8 x6 = lds_rd128<128>(a6), y6 = lds_rd128<12416>(a6);
;   asm volatile("s_waitcnt lgkmcnt(2)" ::: "memory"); SBAR();
;   p0 = __builtin_amdgcn_mfma_f32_32x32x16_bf16(x5, qr[5], p0, 0, 0, 0); p1 = __builtin_amdgcn_mfma_f32_32x32x16_bf16(y5, qr[5], p1, 0, 0, 0);
;   const int a7 = kb ^ (3 << 5); const bf16x8 x7 = lds_rd128<128>(a7), y7 = lds_rd128<12416>(a7);
;   asm volatile("s_waitcnt lgkmcnt(2)" ::: "memory"); SBAR();
;   p0 = __builtin_amdgcn_mfma_f32_32x32x16_bf16(x6, qr[6], p0, 0, 0, 0); p1 = __builtin_amdgcn_mfma_f32_32x32x16_bf16(y6, qr[6], p1, 0, 0, 0);
.LBB0_392:
	v_xor_b32_e32 v66, 0x80000000, v225
	v_cndmask_b32_e64 v228, v66, v228, s[6:7]
	v_exp_f32_e32 v166, v114
	v_exp_f32_e32 v167, v116
	v_exp_f32_e32 v165, v124
	v_exp_f32_e32 v163, v126
	v_exp_f32_e32 v162, v128
	v_exp_f32_e32 v164, v129
	v_cmp_neq_f32_e64 s[6:7], v228, -v227
	s_cmp_eq_u64 s[6:7], 0
	s_cselect_b64 s[6:7], -1, 0
	s_cbranch_scc1 .Lmy_negm_skip_1
	v_cndmask_b32_e64 v113, -v227, v113, s[6:7]
	v_cndmask_b32_e64 v112, -v227, v112, s[6:7]
	v_cndmask_b32_e64 v111, -v227, v111, s[6:7]
	v_cndmask_b32_e64 v110, -v227, v110, s[6:7]
	v_cndmask_b32_e64 v109, -v227, v109, s[6:7]
	v_cndmask_b32_e64 v108, -v227, v108, s[6:7]
	v_cndmask_b32_e64 v107, -v227, v107, s[6:7]
	v_cndmask_b32_e64 v106, -v227, v106, s[6:7]
	v_cndmask_b32_e64 v105, -v227, v105, s[6:7]
	v_cndmask_b32_e64 v104, -v227, v104, s[6:7]
	v_cndmask_b32_e64 v103, -v227, v103, s[6:7]
	v_cndmask_b32_e64 v102, -v227, v102, s[6:7]
	v_cndmask_b32_e64 v101, -v227, v101, s[6:7]
	v_cndmask_b32_e64 v100, -v227, v100, s[6:7]
	v_cndmask_b32_e64 v99, -v227, v99, s[6:7]
	v_cndmask_b32_e64 v98, -v227, v98, s[6:7]
.Lmy_negm_skip_1:
	v_exp_f32_e32 v177, v115
	v_exp_f32_e32 v176, v117
	v_exp_f32_e32 v168, v118
	v_exp_f32_e32 v175, v119
	v_exp_f32_e32 v169, v120
	v_exp_f32_e32 v174, v121
	v_exp_f32_e32 v170, v122
	v_exp_f32_e32 v173, v123
	v_exp_f32_e32 v171, v125
	v_exp_f32_e32 v172, v127
	s_waitcnt lgkmcnt(0)
	s_barrier
	ds_read_b128 v[66:69], v209 offset:0
	ds_read_b128 v[178:181], v209 offset:0x3000
	ds_read_b128 v[230:233], v215 offset:0
	ds_read_b128 v[234:237], v215 offset:0x3000
	s_waitcnt lgkmcnt(2)
	s_nop 0
	v_mfma_f32_32x32x16_bf16 v[114:129], v[66:69], v[158:161], v[98:113]
	v_mfma_f32_32x32x16_bf16 v[66:81], v[178:181], v[158:161], v[98:113]
	ds_read_b128 v[178:181], v216 offset:0
	ds_read_b128 v[238:241], v216 offset:0x3000
	s_waitcnt lgkmcnt(2)
	v_mfma_f32_32x32x16_bf16 v[114:129], v[230:233], v[154:157], v[114:129]
	ds_read_b128 v[230:233], v217 offset:0
	v_mfma_f32_32x32x16_bf16 v[66:81], v[234:237], v[154:157], v[66:81]
	ds_read_b128 v[234:237], v217 offset:0x3000
	s_waitcnt lgkmcnt(2)
	v_mfma_f32_32x32x16_bf16 v[114:129], v[178:181], v[150:153], v[114:129]
	ds_read_b128 v[178:181], v209 offset:0x80
	v_mfma_f32_32x32x16_bf16 v[66:81], v[238:241], v[150:153], v[66:81]
	ds_read_b128 v[238:241], v209 offset:0x3080
	s_waitcnt lgkmcnt(2)
	v_mfma_f32_32x32x16_bf16 v[114:129], v[230:233], v[146:149], v[114:129]
	ds_read_b128 v[230:233], v215 offset:0x80
	v_mfma_f32_32x32x16_bf16 v[66:81], v[234:237], v[146:149], v[66:81]
	ds_read_b128 v[234:237], v215 offset:0x3080
	s_waitcnt lgkmcnt(2)
	v_mfma_f32_32x32x16_bf16 v[114:129], v[178:181], v[142:145], v[114:129]
	ds_read_b128 v[178:181], v216 offset:0x80
	v_mfma_f32_32x32x16_bf16 v[66:81], v[238:241], v[142:145], v[66:81]
	ds_read_b128 v[238:241], v216 offset:0x3080
	s_waitcnt lgkmcnt(2)
	v_mfma_f32_32x32x16_bf16 v[114:129], v[230:233], v[138:141], v[114:129]
	ds_read_b128 v[230:233], v217 offset:0x80
	v_mfma_f32_32x32x16_bf16 v[66:81], v[234:237], v[138:141], v[66:81]
	ds_read_b128 v[234:237], v217 offset:0x3080
	s_waitcnt lgkmcnt(2)
	v_mfma_f32_32x32x16_bf16 v[114:129], v[178:181], v[134:137], v[114:129]
	ds_read_b128 v[178:181], v209 offset:0x100
	v_mfma_f32_32x32x16_bf16 v[66:81], v[238:241], v[134:137], v[66:81]
	ds_read_b128 v[238:241], v209 offset:0x3100
	ds_read_b128 v[242:245], v199 offset:0
	s_waitcnt lgkmcnt(3)
	v_mfma_f32_32x32x16_bf16 v[114:129], v[230:233], v[130:133], v[114:129]
	ds_read_b128 v[230:233], v215 offset:0x100
	v_mfma_f32_32x32x16_bf16 v[66:81], v[234:237], v[130:133], v[66:81]
	ds_read_b128 v[234:237], v215 offset:0x3100
	ds_read_b128 v[246:249], v199 offset:0x400
	s_waitcnt lgkmcnt(3)
	v_mfma_f32_32x32x16_bf16 v[114:129], v[178:181], v[242:245], v[114:129]
	ds_read_b128 v[178:181], v216 offset:0x100
	v_mfma_f32_32x32x16_bf16 v[66:81], v[238:241], v[242:245], v[66:81]
	ds_read_b128 v[238:241], v216 offset:0x3100
	ds_read_b128 v[242:245], v199 offset:0x800
	s_waitcnt lgkmcnt(3)
	v_mfma_f32_32x32x16_bf16 v[114:129], v[230:233], v[246:249], v[114:129]
	ds_read_b128 v[230:233], v217 offset:0x100
	v_mfma_f32_32x32x16_bf16 v[66:81], v[234:237], v[246:249], v[66:81]
	ds_read_b128 v[234:237], v217 offset:0x3100
	ds_read_b128 v[246:249], v199 offset:0xc00
	s_waitcnt lgkmcnt(3)
	v_mfma_f32_32x32x16_bf16 v[114:129], v[178:181], v[242:245], v[114:129]
	s_waitcnt lgkmcnt(0)
; __device__ __forceinline__ void pv_d0(f32x16* o, int vb, bf16x8 pa0, bf16x8 pa1, bf16x8 pa2, bf16x8 pa3) {
;     ...
;   const s16x4 l0 = tr_read<v_rd_off(0, 0, 0)>(vb), h0 = tr_read<v_rd_off(0, 0, 1)>(vb);
;   const s16x4 l1 = tr_read<v_rd_off(0, 1, 0)>(vb), h1 = tr_read<v_rd_off(0, 1, 1)>(vb);
;   const s16x4 l2 = tr_read<v_rd_off(0, 2, 0)>(vb), h2 = tr_read<v_rd_off(0, 2, 1)>(vb);
;   const s16x4 l3 = tr_read<v_rd_off(0, 3, 0)>(vb), h3 = tr_read<v_rd_off(0, 3, 1)>(vb);
;   const s16x4 l4 = tr_read<v_rd_off(1, 0, 0)>(vb), h4 = tr_read<v_rd_off(1, 0, 1)>(vb);
;   asm volatile("s_waitcnt lgkmcnt(8)" ::: "memory"); SBAR();
;   o[0] = __builtin_amdgcn_mfma_f32_32x32x16_bf16(pa0, PK(l0, h0), o[0], 0, 0, 0);
;   const s16x4 l5 = tr_read<v_rd_off(1, 1, 0)>(vb), h5 = tr_read<v_rd_off(1, 1, 1)>(vb);
;   asm volatile("s_waitcnt lgkmcnt(8)" ::: "memory"); SBAR();
;   o[0] = __builtin_amdgcn_mfma_f32_32x32x16_bf16(pa1, PK(l1, h1), o[0], 0, 0, 0);
;   const s16x4 l6 = tr_read<v_rd_off(1, 2, 0)>(vb), h6 = tr_read<v_rd_off(1, 2, 1)>(vb);
;   asm volatile("s_waitcnt lgkmcnt(8)" ::: "memory"); SBAR();
;   o[0] = __builtin_amdgcn_mfma_f32_32x32x16_bf16(pa2, PK(l2, h2), o[0], 0, 0, 0);
;   const s16x4 l7 = tr_read<v_rd_off(1, 3, 0)>(vb), h7 = tr_read<v_rd_off(1, 3, 1)>(vb);
;   asm volatile("s_waitcnt lgkmcnt(8)" ::: "memory"); SBAR();
;   o[0] = __builtin_amdgcn_mfma_f32_32x32x16_bf16(pa3, PK(l3, h3), o[0], 0, 0, 0);
;   const s16x4 l8 = tr_read<v_rd_off(2, 0, 0)>(vb), h8 = tr_read<v_rd_off(2, 0, 1)>(vb);
;   asm volatile("s_waitcnt lgkmcnt(8)" ::: "memory"); SBAR();
;   o[1] = __builtin_amdgcn_mfma_f32_32x32x16_bf16(pa0, PK(l4, h4), o[1], 0, 0, 0);
;   const s16x4 l9 = tr_read<v_rd_off(2, 1, 0)>(vb), h9 = tr_read<v_rd_off(2, 1, 1)>(vb);
;   asm volatile("s_waitcnt lgkmcnt(8)" ::: "memory"); SBAR();
;   o[1] = __builtin_amdgcn_mfma_f32_32x32x16_bf16(pa1, PK(l5, h5), o[1], 0, 0, 0);
;   const s16x4 l10 = tr_read<v_rd_off(2, 2, 0)>(vb), h10 = tr_read<v_rd_off(2, 2, 1)>(vb);
;   asm volatile("s_waitcnt lgkmcnt(8)" ::: "memory"); SBAR();
;   o[1] = __builtin_amdgcn_mfma_f32_32x32x16_bf16(pa2, PK(l6, h6), o[1], 0, 0, 0);
;   const s16x4 l11 = tr_read<v_rd_off(2, 3, 0)>(vb), h11 = tr_read<v_rd_off(2, 3, 1)>(vb);
;   asm volatile("s_waitcnt lgkmcnt(8)" ::: "memory"); SBAR();
;   o[1] = __builtin_amdgcn_mfma_f32_32x32x16_bf16(pa3, PK(l7, h7), o[1], 0, 0, 0);
	v_mfma_f32_32x32x16_bf16 v[66:81], v[238:241], v[242:245], v[66:81]
	v_mfma_f32_32x32x16_bf16 v[114:129], v[230:233], v[246:249], v[114:129]
	v_mfma_f32_32x32x16_bf16 v[66:81], v[234:237], v[246:249], v[66:81]
	v_exp_f32_e32 v82, v82
	v_exp_f32_e32 v83, v83
	v_exp_f32_e32 v84, v84
	v_exp_f32_e32 v85, v85
	v_exp_f32_e32 v86, v86
	v_exp_f32_e32 v87, v87
	v_exp_f32_e32 v88, v88
	v_exp_f32_e32 v89, v89
	v_add_f32_e32 v178, v168, v166
	v_add_f32_e32 v179, v175, v177
	v_add_f32_e32 v180, v169, v167
	v_add_f32_e32 v181, v174, v176
	v_exp_f32_e32 v90, v90
	v_exp_f32_e32 v91, v91
	v_exp_f32_e32 v92, v92
	v_exp_f32_e32 v93, v93
	v_add_f32_e32 v178, v170, v178
	v_add_f32_e32 v179, v173, v179
	v_add_f32_e32 v180, v165, v180
	v_add_f32_e32 v181, v171, v181
	v_exp_f32_e32 v94, v94
	v_exp_f32_e32 v95, v95
	v_exp_f32_e32 v96, v96
	v_exp_f32_e32 v97, v97
	v_add_f32_e32 v178, v163, v178
	v_add_f32_e32 v179, v172, v179
	v_add_f32_e32 v180, v162, v180
	v_add_f32_e32 v181, v164, v181
	v_add_f32_e32 v178, v82, v178
	v_add_f32_e32 v179, v179, v83
	v_add_f32_e32 v180, v180, v84
	v_add_f32_e32 v181, v181, v85
	v_add_f32_e32 v178, v86, v178
	v_add_f32_e32 v179, v87, v179
	v_add_f32_e32 v180, v88, v180
	v_add_f32_e32 v181, v89, v181
	v_add_f32_e32 v178, v90, v178
	v_add_f32_e32 v179, v91, v179
	v_add_f32_e32 v180, v92, v180
	v_add_f32_e32 v181, v93, v181
	v_add_f32_e32 v178, v94, v178
	v_add_f32_e32 v179, v95, v179
	v_add_f32_e32 v180, v96, v180
	v_add_f32_e32 v181, v97, v181
	v_add_f32_e32 v178, v178, v179
	v_add_f32_e32 v179, v180, v181
	v_add_f32_e32 v229, v178, v179
	v_mov_b32_e32 v230, v229
	v_cvt_pk_bf16_f32 v166, v166, v177
	v_cvt_pk_bf16_f32 v167, v167, v176
	v_cvt_pk_bf16_f32 v168, v168, v175
	v_cvt_pk_bf16_f32 v169, v169, v174
	s_nop 1
	v_permlane32_swap_b32_e32 v229, v230
	v_cvt_pk_bf16_f32 v170, v170, v173
	v_cvt_pk_bf16_f32 v171, v165, v171
	v_cvt_pk_bf16_f32 v172, v163, v172
	v_cvt_pk_bf16_f32 v173, v162, v164
	v_cvt_pk_bf16_f32 v174, v82, v83
	v_cvt_pk_bf16_f32 v175, v84, v85
	v_cvt_pk_bf16_f32 v176, v86, v87
	v_cvt_pk_bf16_f32 v177, v88, v89
	v_cvt_pk_bf16_f32 v178, v90, v91
	v_cvt_pk_bf16_f32 v179, v92, v93
	v_cvt_pk_bf16_f32 v180, v94, v95
	v_cvt_pk_bf16_f32 v181, v96, v97
	s_nop 0
	v_add_co_u32_e32 v86, vcc, s69, v190
	s_nop 1
	v_addc_co_u32_e32 v87, vcc, 0, v191, vcc
	v_add_co_u32_e32 v90, vcc, s74, v190
	s_nop 1
	v_addc_co_u32_e32 v91, vcc, 0, v191, vcc
	global_load_dwordx4 v[82:85], v[86:87], off offset:256
	s_nop 0
	global_load_dwordx4 v[86:89], v[86:87], off
	s_nop 0
	global_load_dwordx4 v[94:97], v[90:91], off offset:256
	s_nop 0
	global_load_dwordx4 v[90:93], v[90:91], off
	v_add_co_u32_e32 v162, vcc, s75, v196
	s_nop 1
	v_addc_co_u32_e32 v163, vcc, 0, v197, vcc
	global_load_dwordx4 v[162:165], v[162:163], off
	ds_read_b64_tr_b16 v[232:233], v208 offset:0
	ds_read_b64_tr_b16 v[234:235], v208 offset:0x800
	ds_read_b64_tr_b16 v[236:237], v208 offset:0x1000
	ds_read_b64_tr_b16 v[238:239], v208 offset:0x1800
	ds_read_b64_tr_b16 v[240:241], v208 offset:0x2000
	ds_read_b64_tr_b16 v[242:243], v208 offset:0x2800
	ds_read_b64_tr_b16 v[244:245], v208 offset:0x3000
	ds_read_b64_tr_b16 v[246:247], v208 offset:0x3800
	ds_read_b64_tr_b16 v[248:249], v208 offset:0x200
	ds_read_b64_tr_b16 v[250:251], v208 offset:0xa00
	s_waitcnt lgkmcnt(8)
	s_nop 0
	v_mfma_f32_32x32x16_bf16 v[2:17], v[166:169], v[232:235], v[2:17]
	ds_read_b64_tr_b16 v[232:233], v208 offset:0x1200
	ds_read_b64_tr_b16 v[234:235], v208 offset:0x1a00
	s_waitcnt lgkmcnt(8)
	v_mfma_f32_32x32x16_bf16 v[2:17], v[170:173], v[236:239], v[2:17]
	ds_read_b64_tr_b16 v[236:237], v208 offset:0x2200
	ds_read_b64_tr_b16 v[238:239], v208 offset:0x2a00
	s_waitcnt lgkmcnt(8)
	v_mfma_f32_32x32x16_bf16 v[2:17], v[174:177], v[240:243], v[2:17]
	ds_read_b64_tr_b16 v[240:241], v208 offset:0x3200
	ds_read_b64_tr_b16 v[242:243], v208 offset:0x3a00
	s_waitcnt lgkmcnt(8)
	v_mfma_f32_32x32x16_bf16 v[2:17], v[178:181], v[244:247], v[2:17]
	ds_read_b64_tr_b16 v[244:245], v208 offset:0x400
	ds_read_b64_tr_b16 v[246:247], v208 offset:0xc00
	s_waitcnt lgkmcnt(8)
	v_mfma_f32_32x32x16_bf16 v[50:65], v[166:169], v[248:251], v[50:65]
	ds_read_b64_tr_b16 v[248:249], v208 offset:0x1400
	ds_read_b64_tr_b16 v[250:251], v208 offset:0x1c00
	s_waitcnt lgkmcnt(8)
	v_mfma_f32_32x32x16_bf16 v[50:65], v[170:173], v[232:235], v[50:65]
	ds_read_b64_tr_b16 v[232:233], v208 offset:0x2400
	ds_read_b64_tr_b16 v[234:235], v208 offset:0x2c00
	s_waitcnt lgkmcnt(8)
	v_mfma_f32_32x32x16_bf16 v[50:65], v[174:177], v[236:239], v[50:65]
	ds_read_b64_tr_b16 v[236:237], v208 offset:0x3400
	ds_read_b64_tr_b16 v[238:239], v208 offset:0x3c00
	s_waitcnt lgkmcnt(8)
	v_mfma_f32_32x32x16_bf16 v[50:65], v[178:181], v[240:243], v[50:65]
	ds_read_b64_tr_b16 v[240:241], v208 offset:0x600
	ds_read_b64_tr_b16 v[242:243], v208 offset:0xe00
	s_waitcnt lgkmcnt(8)
	v_mfma_f32_32x32x16_bf16 v[34:49], v[166:169], v[244:247], v[34:49]
	ds_read_b64_tr_b16 v[244:245], v208 offset:0x1600
	ds_read_b64_tr_b16 v[246:247], v208 offset:0x1e00
	s_waitcnt lgkmcnt(8)
	v_mfma_f32_32x32x16_bf16 v[34:49], v[170:173], v[248:251], v[34:49]
	ds_read_b64_tr_b16 v[248:249], v208 offset:0x2600
	ds_read_b64_tr_b16 v[250:251], v208 offset:0x2e00
	s_waitcnt lgkmcnt(8)
	v_mfma_f32_32x32x16_bf16 v[34:49], v[174:177], v[232:235], v[34:49]
	ds_read_b64_tr_b16 v[232:233], v208 offset:0x3600
	ds_read_b64_tr_b16 v[234:235], v208 offset:0x3e00
	s_waitcnt lgkmcnt(8)
	v_mfma_f32_32x32x16_bf16 v[34:49], v[178:181], v[236:239], v[34:49]
	s_waitcnt lgkmcnt(6)
	v_mfma_f32_32x32x16_bf16 v[18:33], v[166:169], v[240:243], v[18:33]
	s_waitcnt lgkmcnt(4)
	v_mfma_f32_32x32x16_bf16 v[18:33], v[170:173], v[244:247], v[18:33]
	s_waitcnt lgkmcnt(2)
	v_mfma_f32_32x32x16_bf16 v[18:33], v[174:177], v[248:251], v[18:33]
	s_waitcnt lgkmcnt(0)
	v_max_f32_e32 v166, v114, v118
	v_max_f32_e32 v167, v115, v119
	v_max_f32_e32 v168, v117, v121
	v_max3_f32 v169, v116, v120, v124
	v_max3_f32 v168, v168, v125, v129
	v_max3_f32 v166, v166, v122, v126
	v_max3_f32 v167, v167, v123, v127
	v_max3_f32 v169, v169, v128, v68
	v_max3_f32 v168, v168, v69, v73
	v_max3_f32 v166, v166, v66, v70
	v_max3_f32 v167, v167, v67, v71
	v_max3_f32 v169, v169, v72, v76
	v_max3_f32 v168, v168, v77, v81
	v_mfma_f32_32x32x16_bf16 v[18:33], v[178:181], v[232:235], v[18:33]
	v_max3_f32 v166, v166, v74, v78
	v_max3_f32 v167, v167, v75, v79
	v_max3_f32 v168, v169, v80, v168
	v_max3_f32 v166, v166, v167, v168
	v_mov_b32_e32 v167, v166
	v_cmp_ge_f32_e32 vcc, s48, v167
	s_cmp_eq_u64 vcc, exec
	v_mov_b32_e32 v166, 1.0
	s_cbranch_scc0 .LBB0_401
	v_mov_b32_e32 v225, v227

; __device__ __forceinline__ void qkt8_roll(f32x16& p0, f32x16& p1, const f32x16& negm, int kb, const bf16x8* qr) {
;   const int a0 = kb ^ (0 << 5); const bf16x8 x0 = lds_rd128<0>(a0), y0 = lds_rd128<8192>(a0);
;   const int a1 = kb ^ (1 << 5); const bf16x8 x1 = lds_rd128<0>(a1), y1 = lds_rd128<8192>(a1);
;   const int a2 = kb ^ (2 << 5); const bf16x8 x2 = lds_rd128<0>(a2), y2 = lds_rd128<8192>(a2);
;   asm volatile("s_waitcnt lgkmcnt(4)" ::: "memory"); SBAR_M();
;   p0 = __builtin_amdgcn_mfma_f32_32x32x16_bf16(x0, qr[0], negm, 0, 0, 0); p1 = __builtin_amdgcn_mfma_f32_32x32x16_bf16(y0, qr[0], negm, 0, 0, 0);
;   const int a3 = kb ^ (3 << 5); const bf16x8 x3 = lds_rd128<0>(a3), y3 = lds_rd128<8192>(a3);
;   asm volatile("s_waitcnt lgkmcnt(4)" ::: "memory"); SBAR_M();
;   p0 = __builtin_amdgcn_mfma_f32_32x32x16_bf16(x1, qr[1], p0, 0, 0, 0); p1 = __builtin_amdgcn_mfma_f32_32x32x16_bf16(y1, qr[1], p1, 0, 0, 0);
;   const int a4 = kb ^ (4 << 5); const bf16x8 x4 = lds_rd128<0>(a4), y4 = lds_rd128<8192>(a4);
;   asm volatile("s_waitcnt lgkmcnt(4)" ::: "memory"); SBAR_M();
;   p0 = __builtin_amdgcn_mfma_f32_32x32x16_bf16(x2, qr[2], p0, 0, 0, 0); p1 = __builtin_amdgcn_mfma_f32_32x32x16_bf16(y2, qr[2], p1, 0, 0, 0);
;   const int a5 = kb ^ (5 << 5); const bf16x8 x5 = lds_rd128<0>(a5), y5 = lds_rd128<8192>(a5);
;   asm volatile("s_waitcnt lgkmcnt(4)" ::: "memory"); SBAR_M();
;   p0 = __builtin_amdgcn_mfma_f32_32x32x16_bf16(x3, qr[3], p0, 0, 0, 0); p1 = __builtin_amdgcn_mfma_f32_32x32x16_bf16(y3, qr[3], p1, 0, 0, 0);
;   const int a6 = kb ^ (6 << 5); const bf16x8 x6 = lds_rd128<0>(a6), y6 = lds_rd128<8192>(a6);
;   asm volatile("s_waitcnt lgkmcnt(4)" ::: "memory"); SBAR_M();
;   p0 = __builtin_amdgcn_mfma_f32_32x32x16_bf16(x4, qr[4], p0, 0, 0, 0); p1 = __builtin_amdgcn_mfma_f32_32x32x16_bf16(y4, qr[4], p1, 0, 0, 0);
;   const int a7 = kb ^ (7 << 5); const bf16x8 x7 = lds_rd128<0>(a7), y7 = lds_rd128<8192>(a7);
;   asm volatile("s_waitcnt lgkmcnt(4)" ::: "memory"); SBAR_M();
;   p0 = __builtin_amdgcn_mfma_f32_32x32x16_bf16(x5, qr[5], p0, 0, 0, 0); p1 = __builtin_amdgcn_mfma_f32_32x32x16_bf16(y5, qr[5], p1, 0, 0, 0);
;   asm volatile("s_waitcnt lgkmcnt(2)" ::: "memory"); SBAR_M();
;   p0 = __builtin_amdgcn_mfma_f32_32x32x16_bf16(x6, qr[6], p0, 0, 0, 0); p1 = __builtin_amdgcn_mfma_f32_32x32x16_bf16(y6, qr[6], p1, 0, 0, 0);
.LBB0_421:
	v_exp_f32_e32 v66, v66
	v_exp_f32_e32 v67, v67
	v_exp_f32_e32 v68, v68
	v_exp_f32_e32 v69, v69
	v_exp_f32_e32 v70, v70
	v_exp_f32_e32 v71, v71
	v_exp_f32_e32 v72, v72
	v_exp_f32_e32 v73, v73
	v_add_f32_e32 v98, v148, v146
	v_add_f32_e32 v99, v159, v161
	v_add_f32_e32 v100, v149, v147
	v_add_f32_e32 v101, v158, v160
	v_exp_f32_e32 v74, v74
	v_exp_f32_e32 v75, v75
	v_exp_f32_e32 v76, v76
	v_exp_f32_e32 v77, v77
	v_add_f32_e32 v98, v150, v98
	v_add_f32_e32 v99, v157, v99
	v_add_f32_e32 v100, v151, v100
	v_add_f32_e32 v101, v156, v101
	v_exp_f32_e32 v78, v78
	v_exp_f32_e32 v79, v79
	v_exp_f32_e32 v80, v80
	v_exp_f32_e32 v81, v81
	v_add_f32_e32 v98, v152, v98
	v_add_f32_e32 v99, v155, v99
	v_add_f32_e32 v100, v153, v100
	v_add_f32_e32 v101, v154, v101
	v_add_f32_e32 v98, v66, v98
	v_add_f32_e32 v99, v67, v99
	v_add_f32_e32 v100, v68, v100
	v_add_f32_e32 v101, v69, v101
	v_add_f32_e32 v98, v70, v98
	v_add_f32_e32 v99, v71, v99
	v_add_f32_e32 v100, v72, v100
	v_add_f32_e32 v101, v73, v101
	v_add_f32_e32 v98, v74, v98
	v_add_f32_e32 v99, v75, v99
	v_add_f32_e32 v100, v76, v100
	v_add_f32_e32 v101, v77, v101
	v_add_f32_e32 v98, v78, v98
	v_add_f32_e32 v99, v79, v99
	v_add_f32_e32 v100, v80, v100
	v_add_f32_e32 v101, v81, v101
	v_add_f32_e32 v98, v98, v99
	v_add_f32_e32 v99, v100, v101
	v_add_f32_e32 v228, v98, v99
	v_mov_b32_e32 v229, v228
	v_cvt_pk_bf16_f32 v146, v146, v161
	v_cvt_pk_bf16_f32 v147, v147, v160
	v_cvt_pk_bf16_f32 v148, v148, v159
	v_cvt_pk_bf16_f32 v149, v149, v158
	v_cvt_pk_bf16_f32 v150, v150, v157
	v_cvt_pk_bf16_f32 v151, v151, v156
	v_cvt_pk_bf16_f32 v152, v152, v155
	v_cvt_pk_bf16_f32 v153, v153, v154
	v_cvt_pk_bf16_f32 v158, v66, v67
	v_cvt_pk_bf16_f32 v159, v68, v69
	v_cvt_pk_bf16_f32 v160, v70, v71
	v_cvt_pk_bf16_f32 v161, v72, v73
	v_cvt_pk_bf16_f32 v154, v74, v75
	v_cvt_pk_bf16_f32 v155, v76, v77
	v_cvt_pk_bf16_f32 v156, v78, v79
	v_cvt_pk_bf16_f32 v157, v80, v81
	s_nop 1
	v_permlane32_swap_b32_e32 v228, v229
	v_cmp_neq_f32_e64 s[6:7], v232, -v227
	s_cmp_eq_u64 s[6:7], 0
	s_cselect_b64 s[6:7], -1, 0
	s_cbranch_scc0 .Lmy_negm_slow_2
	v_mov_b64_e32 v[66:67], v[82:83]
	v_mov_b64_e32 v[68:69], v[84:85]
	v_mov_b64_e32 v[70:71], v[86:87]
	v_mov_b64_e32 v[72:73], v[88:89]
	v_mov_b64_e32 v[74:75], v[90:91]
	v_mov_b64_e32 v[76:77], v[92:93]
	v_mov_b64_e32 v[78:79], v[94:95]
	v_mov_b64_e32 v[80:81], v[96:97]
.Lmy_negm_back_2:
	ds_read_b128 v[82:85], v224 offset:0
	ds_read_b128 v[162:165], v224 offset:0x2000
	ds_read_b128 v[166:169], v223 offset:0
	ds_read_b128 v[170:173], v223 offset:0x2000
	ds_read_b128 v[174:177], v222 offset:0
	ds_read_b128 v[188:191], v222 offset:0x2000
	s_waitcnt lgkmcnt(4)
	s_nop 1
	v_mfma_f32_32x32x16_bf16 v[98:113], v[82:85], v[142:145], v[66:81]
	v_mfma_f32_32x32x16_bf16 v[82:97], v[162:165], v[142:145], v[66:81]
	ds_read_b128 v[162:165], v221 offset:0
	ds_read_b128 v[192:195], v221 offset:0x2000
	s_waitcnt lgkmcnt(4)
	v_mfma_f32_32x32x16_bf16 v[98:113], v[166:169], v[138:141], v[98:113]
	ds_read_b128 v[166:169], v220 offset:0
	v_mfma_f32_32x32x16_bf16 v[82:97], v[170:173], v[138:141], v[82:97]
	ds_read_b128 v[170:173], v220 offset:0x2000
	s_waitcnt lgkmcnt(4)
	v_mfma_f32_32x32x16_bf16 v[98:113], v[174:177], v[134:137], v[98:113]
	ds_read_b128 v[174:177], v219 offset:0
	v_mfma_f32_32x32x16_bf16 v[82:97], v[188:191], v[134:137], v[82:97]
	ds_read_b128 v[188:191], v219 offset:0x2000
	s_waitcnt lgkmcnt(4)
	v_mfma_f32_32x32x16_bf16 v[98:113], v[162:165], v[130:133], v[98:113]
	ds_read_b128 v[162:165], v218 offset:0
	v_mfma_f32_32x32x16_bf16 v[82:97], v[192:195], v[130:133], v[82:97]
	ds_read_b128 v[192:195], v218 offset:0x2000
	s_waitcnt lgkmcnt(4)
	v_mfma_f32_32x32x16_bf16 v[98:113], v[166:169], v[126:129], v[98:113]
	ds_read_b128 v[166:169], v217 offset:0
	v_mfma_f32_32x32x16_bf16 v[82:97], v[170:173], v[126:129], v[82:97]
	ds_read_b128 v[170:173], v217 offset:0x2000
	s_waitcnt lgkmcnt(4)
	v_mfma_f32_32x32x16_bf16 v[98:113], v[174:177], v[122:125], v[98:113]
	s_waitcnt lgkmcnt(2)
	v_mfma_f32_32x32x16_bf16 v[82:97], v[188:191], v[122:125], v[82:97]
	v_mfma_f32_32x32x16_bf16 v[98:113], v[162:165], v[118:121], v[98:113]
	s_waitcnt lgkmcnt(0)
	v_mfma_f32_32x32x16_bf16 v[82:97], v[192:195], v[118:121], v[82:97]
	v_mfma_f32_32x32x16_bf16 v[98:113], v[166:169], v[114:117], v[98:113]
	v_mfma_f32_32x32x16_bf16 v[82:97], v[170:173], v[114:117], v[82:97]
	s_nop 10
	v_max_f32_e32 v162, v98, v102
	v_max_f32_e32 v163, v99, v103
	v_max_f32_e32 v164, v101, v105
	v_max3_f32 v165, v100, v104, v108
	v_max3_f32 v164, v164, v109, v113
	v_max3_f32 v162, v162, v106, v110
	v_max3_f32 v163, v163, v107, v111
	v_max3_f32 v165, v165, v112, v84
	v_max3_f32 v164, v164, v85, v89
	v_max3_f32 v162, v162, v82, v86
	v_max3_f32 v163, v163, v83, v87
	v_max3_f32 v165, v165, v88, v92
	v_max3_f32 v164, v164, v93, v97
	v_max3_f32 v162, v162, v90, v94
	v_max3_f32 v163, v163, v91, v95
	v_max3_f32 v164, v165, v96, v164
	v_max3_f32 v162, v162, v163, v164
	v_cmp_ge_f32_e32 vcc, s48, v162
	s_cmp_eq_u64 vcc, exec
	s_cbranch_scc0 .LBB0_435
	v_mov_b32_e32 v231, v227
	v_mov_b32_e32 v230, 1.0

; __device__ __forceinline__ void qkt8_roll(f32x16& p0, f32x16& p1, const f32x16& negm, int kb, const bf16x8* qr) {
;   const int a0 = kb ^ (0 << 5); const bf16x8 x0 = lds_rd128<0>(a0), y0 = lds_rd128<8192>(a0);
;   const int a1 = kb ^ (1 << 5); const bf16x8 x1 = lds_rd128<0>(a1), y1 = lds_rd128<8192>(a1);
;   const int a2 = kb ^ (2 << 5); const bf16x8 x2 = lds_rd128<0>(a2), y2 = lds_rd128<8192>(a2);
;   asm volatile("s_waitcnt lgkmcnt(4)" ::: "memory"); SBAR_M();
;   p0 = __builtin_amdgcn_mfma_f32_32x32x16_bf16(x0, qr[0], negm, 0, 0, 0); p1 = __builtin_amdgcn_mfma_f32_32x32x16_bf16(y0, qr[0], negm, 0, 0, 0);
;   const int a3 = kb ^ (3 << 5); const bf16x8 x3 = lds_rd128<0>(a3), y3 = lds_rd128<8192>(a3);
;   asm volatile("s_waitcnt lgkmcnt(4)" ::: "memory"); SBAR_M();
;   p0 = __builtin_amdgcn_mfma_f32_32x32x16_bf16(x1, qr[1], p0, 0, 0, 0); p1 = __builtin_amdgcn_mfma_f32_32x32x16_bf16(y1, qr[1], p1, 0, 0, 0);
;   const int a4 = kb ^ (4 << 5); const bf16x8 x4 = lds_rd128<0>(a4), y4 = lds_rd128<8192>(a4);
;   asm volatile("s_waitcnt lgkmcnt(4)" ::: "memory"); SBAR_M();
;   p0 = __builtin_amdgcn_mfma_f32_32x32x16_bf16(x2, qr[2], p0, 0, 0, 0); p1 = __builtin_amdgcn_mfma_f32_32x32x16_bf16(y2, qr[2], p1, 0, 0, 0);
;   const int a5 = kb ^ (5 << 5); const bf16x8 x5 = lds_rd128<0>(a5), y5 = lds_rd128<8192>(a5);
;   asm volatile("s_waitcnt lgkmcnt(4)" ::: "memory"); SBAR_M();
;   p0 = __builtin_amdgcn_mfma_f32_32x32x16_bf16(x3, qr[3], p0, 0, 0, 0); p1 = __builtin_amdgcn_mfma_f32_32x32x16_bf16(y3, qr[3], p1, 0, 0, 0);
;   const int a6 = kb ^ (6 << 5); const bf16x8 x6 = lds_rd128<0>(a6), y6 = lds_rd128<8192>(a6);
;   asm volatile("s_waitcnt lgkmcnt(4)" ::: "memory"); SBAR_M();
;   p0 = __builtin_amdgcn_mfma_f32_32x32x16_bf16(x4, qr[4], p0, 0, 0, 0); p1 = __builtin_amdgcn_mfma_f32_32x32x16_bf16(y4, qr[4], p1, 0, 0, 0);
;   const int a7 = kb ^ (7 << 5); const bf16x8 x7 = lds_rd128<0>(a7), y7 = lds_rd128<8192>(a7);
;   asm volatile("s_waitcnt lgkmcnt(4)" ::: "memory"); SBAR_M();
;   p0 = __builtin_amdgcn_mfma_f32_32x32x16_bf16(x5, qr[5], p0, 0, 0, 0); p1 = __builtin_amdgcn_mfma_f32_32x32x16_bf16(y5, qr[5], p1, 0, 0, 0);
;   asm volatile("s_waitcnt lgkmcnt(2)" ::: "memory"); SBAR_M();
;   p0 = __builtin_amdgcn_mfma_f32_32x32x16_bf16(x6, qr[6], p0, 0, 0, 0); p1 = __builtin_amdgcn_mfma_f32_32x32x16_bf16(y6, qr[6], p1, 0, 0, 0);
.LBB0_427:
	v_exp_f32_e32 v146, v98
	v_exp_f32_e32 v153, v99
	v_exp_f32_e32 v147, v100
	v_exp_f32_e32 v152, v101
	v_exp_f32_e32 v148, v102
	v_exp_f32_e32 v151, v103
	v_exp_f32_e32 v149, v104
	v_exp_f32_e32 v150, v105
	v_exp_f32_e32 v103, v106
	v_exp_f32_e32 v105, v107
	v_exp_f32_e32 v101, v108
	v_exp_f32_e32 v104, v109
	v_exp_f32_e32 v99, v110
	v_exp_f32_e32 v102, v111
	v_exp_f32_e32 v98, v112
	v_exp_f32_e32 v100, v113
	v_xor_b32_e32 v106, 0x80000000, v227
	v_exp_f32_e32 v82, v82
	v_exp_f32_e32 v83, v83
	v_exp_f32_e32 v84, v84
	v_exp_f32_e32 v85, v85
	v_cndmask_b32_e64 v232, v106, v232, s[6:7]
	v_exp_f32_e32 v86, v86
	v_exp_f32_e32 v87, v87
	v_exp_f32_e32 v88, v88
	v_exp_f32_e32 v89, v89
	v_add_f32_e32 v106, v148, v146
	v_add_f32_e32 v107, v151, v153
	v_add_f32_e32 v108, v149, v147
	v_add_f32_e32 v109, v150, v152
	v_exp_f32_e32 v90, v90
	v_exp_f32_e32 v91, v91
	v_exp_f32_e32 v92, v92
	v_exp_f32_e32 v93, v93
	v_add_f32_e32 v106, v103, v106
	v_add_f32_e32 v107, v105, v107
	v_add_f32_e32 v108, v101, v108
	v_add_f32_e32 v109, v104, v109
	v_exp_f32_e32 v94, v94
	v_exp_f32_e32 v95, v95
	v_exp_f32_e32 v96, v96
	v_exp_f32_e32 v97, v97
	v_add_f32_e32 v106, v99, v106
	v_add_f32_e32 v107, v102, v107
	v_add_f32_e32 v108, v98, v108
	v_add_f32_e32 v109, v100, v109
	v_add_f32_e32 v106, v82, v106
	v_add_f32_e32 v107, v107, v83
	v_add_f32_e32 v108, v108, v84
	v_add_f32_e32 v109, v109, v85
	v_add_f32_e32 v106, v86, v106
	v_add_f32_e32 v107, v87, v107
	v_add_f32_e32 v108, v88, v108
	v_add_f32_e32 v109, v89, v109
	v_add_f32_e32 v106, v90, v106
	v_add_f32_e32 v107, v91, v107
	v_add_f32_e32 v108, v92, v108
	v_add_f32_e32 v109, v93, v109
	v_add_f32_e32 v106, v94, v106
	v_add_f32_e32 v107, v95, v107
	v_add_f32_e32 v108, v96, v108
	v_add_f32_e32 v109, v97, v109
	v_add_f32_e32 v106, v106, v107
	v_add_f32_e32 v107, v108, v109
	v_add_f32_e32 v233, v106, v107
	s_waitcnt lgkmcnt(0)
	s_barrier
	v_mov_b32_e32 v234, v233
	v_cvt_pk_bf16_f32 v146, v146, v153
	v_cvt_pk_bf16_f32 v147, v147, v152
	v_cvt_pk_bf16_f32 v148, v148, v151
	v_cvt_pk_bf16_f32 v149, v149, v150
	v_cvt_pk_bf16_f32 v150, v103, v105
	v_cvt_pk_bf16_f32 v151, v101, v104
	v_cvt_pk_bf16_f32 v152, v99, v102
	v_cvt_pk_bf16_f32 v153, v98, v100
	v_cvt_pk_bf16_f32 v158, v82, v83
	v_cvt_pk_bf16_f32 v159, v84, v85
	v_cvt_pk_bf16_f32 v160, v86, v87
	v_cvt_pk_bf16_f32 v161, v88, v89
	v_cvt_pk_bf16_f32 v154, v90, v91
	v_cvt_pk_bf16_f32 v155, v92, v93
	v_cvt_pk_bf16_f32 v156, v94, v95
	v_cvt_pk_bf16_f32 v157, v96, v97
	s_nop 1
	v_permlane32_swap_b32_e32 v233, v234
	v_cmp_neq_f32_e64 s[6:7], v232, -v231
	s_cmp_eq_u64 s[6:7], 0
	s_cselect_b64 s[6:7], -1, 0
	s_cbranch_scc0 .Lmy_negm_slow_3
	v_mov_b64_e32 v[82:83], v[66:67]
	v_mov_b64_e32 v[84:85], v[68:69]
	v_mov_b64_e32 v[86:87], v[70:71]
	v_mov_b64_e32 v[88:89], v[72:73]
	v_mov_b64_e32 v[90:91], v[74:75]
	v_mov_b64_e32 v[92:93], v[76:77]
	v_mov_b64_e32 v[94:95], v[78:79]
	v_mov_b64_e32 v[96:97], v[80:81]
.Lmy_negm_back_3:
	ds_read_b128 v[66:69], v200 offset:0
	ds_read_b128 v[162:165], v200 offset:0x2000
	ds_read_b128 v[166:169], v210 offset:0
	ds_read_b128 v[170:173], v210 offset:0x2000
	ds_read_b128 v[174:177], v211 offset:0
	ds_read_b128 v[192:195], v211 offset:0x2000
	s_waitcnt lgkmcnt(4)
	s_nop 1
	v_mfma_f32_32x32x16_bf16 v[98:113], v[66:69], v[142:145], v[82:97]
	v_mfma_f32_32x32x16_bf16 v[66:81], v[162:165], v[142:145], v[82:97]
	ds_read_b128 v[162:165], v212 offset:0
	ds_read_b128 v[236:239], v212 offset:0x2000
	s_waitcnt lgkmcnt(4)
	v_mfma_f32_32x32x16_bf16 v[98:113], v[166:169], v[138:141], v[98:113]
	ds_read_b128 v[166:169], v213 offset:0
	v_mfma_f32_32x32x16_bf16 v[66:81], v[170:173], v[138:141], v[66:81]
	ds_read_b128 v[170:173], v213 offset:0x2000
	s_waitcnt lgkmcnt(4)
	v_mfma_f32_32x32x16_bf16 v[98:113], v[174:177], v[134:137], v[98:113]
	ds_read_b128 v[174:177], v214 offset:0
	v_mfma_f32_32x32x16_bf16 v[66:81], v[192:195], v[134:137], v[66:81]
	ds_read_b128 v[192:195], v214 offset:0x2000
	s_waitcnt lgkmcnt(4)
	v_mfma_f32_32x32x16_bf16 v[98:113], v[162:165], v[130:133], v[98:113]
	ds_read_b128 v[162:165], v215 offset:0
	v_mfma_f32_32x32x16_bf16 v[66:81], v[236:239], v[130:133], v[66:81]
	ds_read_b128 v[236:239], v215 offset:0x2000
	s_waitcnt lgkmcnt(4)
	v_mfma_f32_32x32x16_bf16 v[98:113], v[166:169], v[126:129], v[98:113]
	ds_read_b128 v[166:169], v216 offset:0
	v_mfma_f32_32x32x16_bf16 v[66:81], v[170:173], v[126:129], v[66:81]
	ds_read_b128 v[170:173], v216 offset:0x2000
	s_waitcnt lgkmcnt(4)
	v_mfma_f32_32x32x16_bf16 v[98:113], v[174:177], v[122:125], v[98:113]
	s_waitcnt lgkmcnt(2)
	v_mfma_f32_32x32x16_bf16 v[66:81], v[192:195], v[122:125], v[66:81]
	v_mfma_f32_32x32x16_bf16 v[98:113], v[162:165], v[118:121], v[98:113]
	s_waitcnt lgkmcnt(0)
	v_mfma_f32_32x32x16_bf16 v[66:81], v[236:239], v[118:121], v[66:81]
	v_mfma_f32_32x32x16_bf16 v[98:113], v[166:169], v[114:117], v[98:113]
	v_mfma_f32_32x32x16_bf16 v[66:81], v[170:173], v[114:117], v[66:81]
	s_nop 10
	v_max_f32_e32 v162, v98, v102
	v_max_f32_e32 v163, v99, v103
	v_max_f32_e32 v164, v101, v105
	v_max3_f32 v165, v100, v104, v108
	v_max3_f32 v164, v164, v109, v113
	v_max3_f32 v162, v162, v106, v110
	v_max3_f32 v163, v163, v107, v111
	v_max3_f32 v165, v165, v112, v68
	v_max3_f32 v164, v164, v69, v73
	v_max3_f32 v162, v162, v66, v70
	v_max3_f32 v163, v163, v67, v71
	v_max3_f32 v165, v165, v72, v76
	v_max3_f32 v164, v164, v77, v81
	v_max3_f32 v162, v162, v74, v78
	v_max3_f32 v163, v163, v75, v79
	v_max3_f32 v164, v165, v80, v164
	v_max3_f32 v162, v162, v163, v164
	v_cmp_ge_f32_e32 vcc, s48, v162
	s_cmp_eq_u64 vcc, exec
	v_mov_b32_e32 v226, 1.0
	s_cbranch_scc0 .LBB0_436
	v_mov_b32_e32 v227, v231

.Lmy_negm_slow_2:
	v_cndmask_b32_e64 v81, -v227, v97, s[6:7]
	v_cndmask_b32_e64 v80, -v227, v96, s[6:7]
	v_cndmask_b32_e64 v79, -v227, v95, s[6:7]
	v_cndmask_b32_e64 v78, -v227, v94, s[6:7]
	v_cndmask_b32_e64 v77, -v227, v93, s[6:7]
	v_cndmask_b32_e64 v76, -v227, v92, s[6:7]
	v_cndmask_b32_e64 v75, -v227, v91, s[6:7]
	v_cndmask_b32_e64 v74, -v227, v90, s[6:7]
	v_cndmask_b32_e64 v73, -v227, v89, s[6:7]
	v_cndmask_b32_e64 v72, -v227, v88, s[6:7]
	v_cndmask_b32_e64 v71, -v227, v87, s[6:7]
	v_cndmask_b32_e64 v70, -v227, v86, s[6:7]
	v_cndmask_b32_e64 v69, -v227, v85, s[6:7]
	v_cndmask_b32_e64 v68, -v227, v84, s[6:7]
	v_cndmask_b32_e64 v67, -v227, v83, s[6:7]
	v_cndmask_b32_e64 v66, -v227, v82, s[6:7]
	s_branch .Lmy_negm_back_2
.Lmy_negm_slow_3:
	v_cndmask_b32_e64 v97, -v231, v81, s[6:7]
	v_cndmask_b32_e64 v96, -v231, v80, s[6:7]
	v_cndmask_b32_e64 v95, -v231, v79, s[6:7]
	v_cndmask_b32_e64 v94, -v231, v78, s[6:7]
	v_cndmask_b32_e64 v93, -v231, v77, s[6:7]
	v_cndmask_b32_e64 v92, -v231, v76, s[6:7]
	v_cndmask_b32_e64 v91, -v231, v75, s[6:7]
	v_cndmask_b32_e64 v90, -v231, v74, s[6:7]
	v_cndmask_b32_e64 v89, -v231, v73, s[6:7]
	v_cndmask_b32_e64 v88, -v231, v72, s[6:7]
	v_cndmask_b32_e64 v87, -v231, v71, s[6:7]
	v_cndmask_b32_e64 v86, -v231, v70, s[6:7]
	v_cndmask_b32_e64 v85, -v231, v69, s[6:7]
	v_cndmask_b32_e64 v84, -v231, v68, s[6:7]
	v_cndmask_b32_e64 v83, -v231, v67, s[6:7]
	v_cndmask_b32_e64 v82, -v231, v66, s[6:7]
	s_branch .Lmy_negm_back_3

; __device__ __forceinline__ void qkt8_roll(f32x16& p0, f32x16& p1, const f32x16& negm, int kb, const bf16x8* qr) {
;   const int a0 = kb ^ (0 << 5); const bf16x8 x0 = lds_rd128<0>(a0), y0 = lds_rd128<8192>(a0);
;   const int a1 = kb ^ (1 << 5); const bf16x8 x1 = lds_rd128<0>(a1), y1 = lds_rd128<8192>(a1);
;   const int a2 = kb ^ (2 << 5); const bf16x8 x2 = lds_rd128<0>(a2), y2 = lds_rd128<8192>(a2);
;   asm volatile("s_waitcnt lgkmcnt(4)" ::: "memory"); SBAR_M();
;   p0 = __builtin_amdgcn_mfma_f32_32x32x16_bf16(x0, qr[0], negm, 0, 0, 0); p1 = __builtin_amdgcn_mfma_f32_32x32x16_bf16(y0, qr[0], negm, 0, 0, 0);
;   const int a3 = kb ^ (3 << 5); const bf16x8 x3 = lds_rd128<0>(a3), y3 = lds_rd128<8192>(a3);
;   asm volatile("s_waitcnt lgkmcnt(4)" ::: "memory"); SBAR_M();
;   p0 = __builtin_amdgcn_mfma_f32_32x32x16_bf16(x1, qr[1], p0, 0, 0, 0); p1 = __builtin_amdgcn_mfma_f32_32x32x16_bf16(y1, qr[1], p1, 0, 0, 0);
;   const int a4 = kb ^ (4 << 5); const bf16x8 x4 = lds_rd128<0>(a4), y4 = lds_rd128<8192>(a4);
;   asm volatile("s_waitcnt lgkmcnt(4)" ::: "memory"); SBAR_M();
;   p0 = __builtin_amdgcn_mfma_f32_32x32x16_bf16(x2, qr[2], p0, 0, 0, 0); p1 = __builtin_amdgcn_mfma_f32_32x32x16_bf16(y2, qr[2], p1, 0, 0, 0);
;   const int a5 = kb ^ (5 << 5); const bf16x8 x5 = lds_rd128<0>(a5), y5 = lds_rd128<8192>(a5);
;   asm volatile("s_waitcnt lgkmcnt(4)" ::: "memory"); SBAR_M();
;   p0 = __builtin_amdgcn_mfma_f32_32x32x16_bf16(x3, qr[3], p0, 0, 0, 0); p1 = __builtin_amdgcn_mfma_f32_32x32x16_bf16(y3, qr[3], p1, 0, 0, 0);
;   const int a6 = kb ^ (6 << 5); const bf16x8 x6 = lds_rd128<0>(a6), y6 = lds_rd128<8192>(a6);
;   asm volatile("s_waitcnt lgkmcnt(4)" ::: "memory"); SBAR_M();
;   p0 = __builtin_amdgcn_mfma_f32_32x32x16_bf16(x4, qr[4], p0, 0, 0, 0); p1 = __builtin_amdgcn_mfma_f32_32x32x16_bf16(y4, qr[4], p1, 0, 0, 0);
;   const int a7 = kb ^ (7 << 5); const bf16x8 x7 = lds_rd128<0>(a7), y7 = lds_rd128<8192>(a7);
;   asm volatile("s_waitcnt lgkmcnt(4)" ::: "memory"); SBAR_M();
;   p0 = __builtin_amdgcn_mfma_f32_32x32x16_bf16(x5, qr[5], p0, 0, 0, 0); p1 = __builtin_amdgcn_mfma_f32_32x32x16_bf16(y5, qr[5], p1, 0, 0, 0);
;   asm volatile("s_waitcnt lgkmcnt(2)" ::: "memory"); SBAR_M();
;   p0 = __builtin_amdgcn_mfma_f32_32x32x16_bf16(x6, qr[6], p0, 0, 0, 0); p1 = __builtin_amdgcn_mfma_f32_32x32x16_bf16(y6, qr[6], p1, 0, 0, 0);
.LBB0_447:
	v_cmp_neq_f32_e64 s[6:7], v231, -v228
	s_cmp_eq_u64 s[6:7], 0
	s_cselect_b64 s[6:7], -1, 0
	s_cbranch_scc1 .Lmy_negm_skip_2
	v_cndmask_b32_e64 v97, -v228, v97, s[6:7]
	v_cndmask_b32_e64 v96, -v228, v96, s[6:7]
	v_cndmask_b32_e64 v95, -v228, v95, s[6:7]
	v_cndmask_b32_e64 v94, -v228, v94, s[6:7]
	v_cndmask_b32_e64 v93, -v228, v93, s[6:7]
	v_cndmask_b32_e64 v92, -v228, v92, s[6:7]
	v_cndmask_b32_e64 v91, -v228, v91, s[6:7]
	v_cndmask_b32_e64 v90, -v228, v90, s[6:7]
	v_cndmask_b32_e64 v89, -v228, v89, s[6:7]
	v_cndmask_b32_e64 v88, -v228, v88, s[6:7]
	v_cndmask_b32_e64 v87, -v228, v87, s[6:7]
	v_cndmask_b32_e64 v86, -v228, v86, s[6:7]
	v_cndmask_b32_e64 v85, -v228, v85, s[6:7]
	v_cndmask_b32_e64 v84, -v228, v84, s[6:7]
	v_cndmask_b32_e64 v83, -v228, v83, s[6:7]
	v_cndmask_b32_e64 v82, -v228, v82, s[6:7]
.Lmy_negm_skip_2:
	ds_read_b128 v[98:101], v224 offset:0
	ds_read_b128 v[232:235], v224 offset:0x2000
	ds_read_b128 v[236:239], v223 offset:0
	ds_read_b128 v[240:243], v223 offset:0x2000
	ds_read_b128 v[244:247], v222 offset:0
	ds_read_b128 v[248:251], v222 offset:0x2000
	s_waitcnt lgkmcnt(4)
	s_nop 1
	v_mfma_f32_32x32x16_bf16 v[114:129], v[98:101], v[158:161], v[82:97]
	v_mfma_f32_32x32x16_bf16 v[98:113], v[232:235], v[158:161], v[82:97]
	ds_read_b128 v[232:235], v221 offset:0
	ds_read_b128 v[190:193], v221 offset:0x2000
	s_waitcnt lgkmcnt(4)
	v_mfma_f32_32x32x16_bf16 v[114:129], v[236:239], v[154:157], v[114:129]
	ds_read_b128 v[236:239], v220 offset:0
	v_mfma_f32_32x32x16_bf16 v[98:113], v[240:243], v[154:157], v[98:113]
	ds_read_b128 v[240:243], v220 offset:0x2000
	s_waitcnt lgkmcnt(4)
	v_mfma_f32_32x32x16_bf16 v[114:129], v[244:247], v[150:153], v[114:129]
	ds_read_b128 v[244:247], v219 offset:0
	v_mfma_f32_32x32x16_bf16 v[98:113], v[248:251], v[150:153], v[98:113]
	ds_read_b128 v[248:251], v219 offset:0x2000
	s_waitcnt lgkmcnt(4)
	v_mfma_f32_32x32x16_bf16 v[114:129], v[232:235], v[146:149], v[114:129]
	v_mfma_f32_32x32x16_bf16 v[98:113], v[190:193], v[146:149], v[98:113]
	ds_read_b128 v[190:193], v218 offset:0
	ds_read_b128 v[232:235], v218 offset:0x2000
	s_waitcnt lgkmcnt(4)
	v_mfma_f32_32x32x16_bf16 v[114:129], v[236:239], v[142:145], v[114:129]
	ds_read_b128 v[236:239], v217 offset:0
	v_mfma_f32_32x32x16_bf16 v[98:113], v[240:243], v[142:145], v[98:113]
	ds_read_b128 v[240:243], v217 offset:0x2000
	s_waitcnt lgkmcnt(4)
	v_mfma_f32_32x32x16_bf16 v[114:129], v[244:247], v[138:141], v[114:129]
	s_waitcnt lgkmcnt(2)
	v_mfma_f32_32x32x16_bf16 v[98:113], v[248:251], v[138:141], v[98:113]
	v_mfma_f32_32x32x16_bf16 v[114:129], v[190:193], v[134:137], v[114:129]
	s_waitcnt lgkmcnt(0)
	v_mfma_f32_32x32x16_bf16 v[98:113], v[232:235], v[134:137], v[98:113]
	v_exp_f32_e32 v66, v66
	v_exp_f32_e32 v67, v67
	v_exp_f32_e32 v68, v68
	v_exp_f32_e32 v69, v69
	v_exp_f32_e32 v70, v70
	v_exp_f32_e32 v71, v71
	v_exp_f32_e32 v72, v72
	v_exp_f32_e32 v73, v73
	v_add_f32_e32 v162, v164, v176
	v_add_f32_e32 v189, v175, v188
	v_add_f32_e32 v190, v165, v163
	v_add_f32_e32 v191, v174, v177
	v_exp_f32_e32 v74, v74
	v_exp_f32_e32 v75, v75
	v_exp_f32_e32 v76, v76
	v_exp_f32_e32 v77, v77
	v_add_f32_e32 v162, v166, v162
	v_add_f32_e32 v189, v173, v189
	v_add_f32_e32 v190, v167, v190
	v_add_f32_e32 v191, v172, v191
	v_exp_f32_e32 v78, v78
	v_exp_f32_e32 v79, v79
	v_exp_f32_e32 v80, v80
	v_exp_f32_e32 v81, v81
	v_add_f32_e32 v162, v168, v162
	v_add_f32_e32 v189, v171, v189
	v_add_f32_e32 v190, v169, v190
	v_add_f32_e32 v191, v170, v191
	v_mfma_f32_32x32x16_bf16 v[114:129], v[236:239], v[130:133], v[114:129]
	v_add_f32_e32 v162, v66, v162
	v_add_f32_e32 v189, v67, v189
	v_add_f32_e32 v190, v68, v190
	v_add_f32_e32 v191, v69, v191
	v_add_f32_e32 v162, v70, v162
	v_add_f32_e32 v189, v71, v189
	v_add_f32_e32 v190, v72, v190
	v_mfma_f32_32x32x16_bf16 v[98:113], v[240:243], v[130:133], v[98:113]
	v_add_f32_e32 v191, v73, v191
	v_add_f32_e32 v162, v74, v162
	v_add_f32_e32 v189, v75, v189
	v_add_f32_e32 v190, v76, v190
	v_add_f32_e32 v191, v77, v191
	v_add_f32_e32 v162, v78, v162
	v_add_f32_e32 v189, v79, v189
	v_add_f32_e32 v190, v80, v190
	v_add_f32_e32 v191, v81, v191
	v_add_f32_e32 v162, v162, v189
	v_add_f32_e32 v189, v190, v191
	v_add_f32_e32 v226, v162, v189
	v_mov_b32_e32 v227, v226
	v_cvt_pk_bf16_f32 v162, v176, v188
	v_cvt_pk_bf16_f32 v163, v163, v177
	v_cvt_pk_bf16_f32 v164, v164, v175
	s_nop 1
	v_permlane32_swap_b32_e32 v226, v227
	v_cvt_pk_bf16_f32 v165, v165, v174
	v_cvt_pk_bf16_f32 v166, v166, v173
	v_cvt_pk_bf16_f32 v167, v167, v172
	v_cvt_pk_bf16_f32 v168, v168, v171
	v_cvt_pk_bf16_f32 v169, v169, v170
	v_cvt_pk_bf16_f32 v170, v66, v67
	v_cvt_pk_bf16_f32 v171, v68, v69
	v_cvt_pk_bf16_f32 v172, v70, v71
	v_cvt_pk_bf16_f32 v173, v72, v73
	v_cvt_pk_bf16_f32 v174, v74, v75
	v_cvt_pk_bf16_f32 v175, v76, v77
	v_cvt_pk_bf16_f32 v176, v78, v79
	v_cvt_pk_bf16_f32 v177, v80, v81
	v_lshl_add_u64 v[188:189], v[186:187], 0, v[0:1]
	v_add_co_u32_e32 v66, vcc, s78, v188
	v_lshl_add_u64 v[190:191], v[184:185], 0, v[0:1]
	s_nop 0
	v_addc_co_u32_e32 v67, vcc, 0, v189, vcc
	v_add_co_u32_e32 v70, vcc, s79, v188
	s_nop 1
	v_addc_co_u32_e32 v71, vcc, 0, v189, vcc
	v_add_co_u32_e32 v74, vcc, s70, v190
	global_load_dwordx4 v[66:69], v[66:67], off offset:2176
	s_nop 0
	global_load_dwordx4 v[70:73], v[70:71], off offset:2176
	v_addc_co_u32_e32 v75, vcc, 0, v191, vcc
	v_add_co_u32_e32 v78, vcc, s71, v190
	s_nop 1
	v_addc_co_u32_e32 v79, vcc, 0, v191, vcc
	global_load_dwordx4 v[74:77], v[74:75], off
	s_nop 0
	global_load_dwordx4 v[78:81], v[78:79], off
	ds_read_b64_tr_b16 v[232:233], v199 offset:0
	ds_read_b64_tr_b16 v[234:235], v199 offset:0x800
	ds_read_b64_tr_b16 v[236:237], v199 offset:0x1000
	ds_read_b64_tr_b16 v[238:239], v199 offset:0x1800
	ds_read_b64_tr_b16 v[240:241], v199 offset:0x2000
	ds_read_b64_tr_b16 v[242:243], v199 offset:0x2800
	ds_read_b64_tr_b16 v[244:245], v199 offset:0x3000
	ds_read_b64_tr_b16 v[246:247], v199 offset:0x3800
	ds_read_b64_tr_b16 v[248:249], v199 offset:0x200
	ds_read_b64_tr_b16 v[250:251], v199 offset:0xa00
	s_waitcnt lgkmcnt(8)
; __device__ __forceinline__ void pv_d0(f32x16* o, int vb, bf16x8 pa0, bf16x8 pa1, bf16x8 pa2, bf16x8 pa3) {
;     ...
;   const s16x4 l0 = tr_read<v_rd_off(0, 0, 0)>(vb), h0 = tr_read<v_rd_off(0, 0, 1)>(vb);
;   const s16x4 l1 = tr_read<v_rd_off(0, 1, 0)>(vb), h1 = tr_read<v_rd_off(0, 1, 1)>(vb);
;   const s16x4 l2 = tr_read<v_rd_off(0, 2, 0)>(vb), h2 = tr_read<v_rd_off(0, 2, 1)>(vb);
;   const s16x4 l3 = tr_read<v_rd_off(0, 3, 0)>(vb), h3 = tr_read<v_rd_off(0, 3, 1)>(vb);
;   const s16x4 l4 = tr_read<v_rd_off(1, 0, 0)>(vb), h4 = tr_read<v_rd_off(1, 0, 1)>(vb);
;   asm volatile("s_waitcnt lgkmcnt(8)" ::: "memory"); SBAR();
;   o[0] = __builtin_amdgcn_mfma_f32_32x32x16_bf16(pa0, PK(l0, h0), o[0], 0, 0, 0);
;   const s16x4 l5 = tr_read<v_rd_off(1, 1, 0)>(vb), h5 = tr_read<v_rd_off(1, 1, 1)>(vb);
;   asm volatile("s_waitcnt lgkmcnt(8)" ::: "memory"); SBAR();
;   o[0] = __builtin_amdgcn_mfma_f32_32x32x16_bf16(pa1, PK(l1, h1), o[0], 0, 0, 0);
;   const s16x4 l6 = tr_read<v_rd_off(1, 2, 0)>(vb), h6 = tr_read<v_rd_off(1, 2, 1)>(vb);
;   asm volatile("s_waitcnt lgkmcnt(8)" ::: "memory"); SBAR();
;   o[0] = __builtin_amdgcn_mfma_f32_32x32x16_bf16(pa2, PK(l2, h2), o[0], 0, 0, 0);
;   const s16x4 l7 = tr_read<v_rd_off(1, 3, 0)>(vb), h7 = tr_read<v_rd_off(1, 3, 1)>(vb);
;   asm volatile("s_waitcnt lgkmcnt(8)" ::: "memory"); SBAR();
;   o[0] = __builtin_amdgcn_mfma_f32_32x32x16_bf16(pa3, PK(l3, h3), o[0], 0, 0, 0);
;   const s16x4 l8 = tr_read<v_rd_off(2, 0, 0)>(vb), h8 = tr_read<v_rd_off(2, 0, 1)>(vb);
;   asm volatile("s_waitcnt lgkmcnt(8)" ::: "memory"); SBAR();
;   o[1] = __builtin_amdgcn_mfma_f32_32x32x16_bf16(pa0, PK(l4, h4), o[1], 0, 0, 0);
;   const s16x4 l9 = tr_read<v_rd_off(2, 1, 0)>(vb), h9 = tr_read<v_rd_off(2, 1, 1)>(vb);
;   asm volatile("s_waitcnt lgkmcnt(8)" ::: "memory"); SBAR();
;   o[1] = __builtin_amdgcn_mfma_f32_32x32x16_bf16(pa1, PK(l5, h5), o[1], 0, 0, 0);
;   const s16x4 l10 = tr_read<v_rd_off(2, 2, 0)>(vb), h10 = tr_read<v_rd_off(2, 2, 1)>(vb);
;   asm volatile("s_waitcnt lgkmcnt(8)" ::: "memory"); SBAR();
;   o[1] = __builtin_amdgcn_mfma_f32_32x32x16_bf16(pa2, PK(l6, h6), o[1], 0, 0, 0);
;   const s16x4 l11 = tr_read<v_rd_off(2, 3, 0)>(vb), h11 = tr_read<v_rd_off(2, 3, 1)>(vb);
;   asm volatile("s_waitcnt lgkmcnt(8)" ::: "memory"); SBAR();
;   o[1] = __builtin_amdgcn_mfma_f32_32x32x16_bf16(pa3, PK(l7, h7), o[1], 0, 0, 0);
	s_nop 0
	v_mfma_f32_32x32x16_bf16 v[2:17], v[162:165], v[232:235], v[2:17]
	ds_read_b64_tr_b16 v[232:233], v199 offset:0x1200
	ds_read_b64_tr_b16 v[234:235], v199 offset:0x1a00
	s_waitcnt lgkmcnt(8)
	v_mfma_f32_32x32x16_bf16 v[2:17], v[166:169], v[236:239], v[2:17]
	ds_read_b64_tr_b16 v[236:237], v199 offset:0x2200
	ds_read_b64_tr_b16 v[238:239], v199 offset:0x2a00
	s_waitcnt lgkmcnt(8)
	v_mfma_f32_32x32x16_bf16 v[2:17], v[170:173], v[240:243], v[2:17]
	ds_read_b64_tr_b16 v[240:241], v199 offset:0x3200
	ds_read_b64_tr_b16 v[242:243], v199 offset:0x3a00
	s_waitcnt lgkmcnt(8)
	v_mfma_f32_32x32x16_bf16 v[2:17], v[174:177], v[244:247], v[2:17]
	ds_read_b64_tr_b16 v[244:245], v199 offset:0x400
	ds_read_b64_tr_b16 v[246:247], v199 offset:0xc00
	s_waitcnt lgkmcnt(8)
	v_mfma_f32_32x32x16_bf16 v[50:65], v[162:165], v[248:251], v[50:65]
	ds_read_b64_tr_b16 v[248:249], v199 offset:0x1400
	ds_read_b64_tr_b16 v[250:251], v199 offset:0x1c00
	s_waitcnt lgkmcnt(8)
	v_mfma_f32_32x32x16_bf16 v[50:65], v[166:169], v[232:235], v[50:65]
	ds_read_b64_tr_b16 v[232:233], v199 offset:0x2400
	ds_read_b64_tr_b16 v[234:235], v199 offset:0x2c00
	s_waitcnt lgkmcnt(8)
	v_mfma_f32_32x32x16_bf16 v[50:65], v[170:173], v[236:239], v[50:65]
	ds_read_b64_tr_b16 v[236:237], v199 offset:0x3400
	ds_read_b64_tr_b16 v[238:239], v199 offset:0x3c00
	s_waitcnt lgkmcnt(8)
	v_mfma_f32_32x32x16_bf16 v[50:65], v[174:177], v[240:243], v[50:65]
	ds_read_b64_tr_b16 v[240:241], v199 offset:0x600
	ds_read_b64_tr_b16 v[242:243], v199 offset:0xe00
	s_waitcnt lgkmcnt(8)
	v_mfma_f32_32x32x16_bf16 v[34:49], v[162:165], v[244:247], v[34:49]
	ds_read_b64_tr_b16 v[244:245], v199 offset:0x1600
	ds_read_b64_tr_b16 v[246:247], v199 offset:0x1e00
	s_waitcnt lgkmcnt(8)
	v_mfma_f32_32x32x16_bf16 v[34:49], v[166:169], v[248:251], v[34:49]
	ds_read_b64_tr_b16 v[248:249], v199 offset:0x2600
	ds_read_b64_tr_b16 v[250:251], v199 offset:0x2e00
	s_waitcnt lgkmcnt(8)
	v_mfma_f32_32x32x16_bf16 v[34:49], v[170:173], v[232:235], v[34:49]
	ds_read_b64_tr_b16 v[232:233], v199 offset:0x3600
	ds_read_b64_tr_b16 v[234:235], v199 offset:0x3e00
	s_waitcnt lgkmcnt(8)
	v_mfma_f32_32x32x16_bf16 v[34:49], v[174:177], v[236:239], v[34:49]
	s_waitcnt lgkmcnt(6)
	v_mfma_f32_32x32x16_bf16 v[18:33], v[162:165], v[240:243], v[18:33]
	s_waitcnt lgkmcnt(4)
	v_mfma_f32_32x32x16_bf16 v[18:33], v[166:169], v[244:247], v[18:33]
	s_waitcnt lgkmcnt(2)
	v_mfma_f32_32x32x16_bf16 v[18:33], v[170:173], v[248:251], v[18:33]
	s_waitcnt lgkmcnt(0)
	v_max_f32_e32 v162, v114, v118
	v_max_f32_e32 v163, v115, v119
	v_max_f32_e32 v164, v117, v121
	v_max3_f32 v165, v116, v120, v124
	v_max3_f32 v164, v164, v125, v129
	v_max3_f32 v162, v162, v122, v126
	v_max3_f32 v163, v163, v123, v127
	v_max3_f32 v165, v165, v128, v100
	v_max3_f32 v164, v164, v101, v105
	v_max3_f32 v162, v162, v98, v102
	v_max3_f32 v163, v163, v99, v103
	v_max3_f32 v165, v165, v104, v108
	v_max3_f32 v164, v164, v109, v113
	v_mfma_f32_32x32x16_bf16 v[18:33], v[174:177], v[232:235], v[18:33]
	v_max3_f32 v162, v162, v106, v110
	v_max3_f32 v163, v163, v107, v111
	v_max3_f32 v164, v165, v112, v164
	v_max3_f32 v162, v162, v163, v164
	v_cmp_ge_f32_e32 vcc, s48, v162
	s_cmp_eq_u64 vcc, exec
	s_cbranch_scc0 .LBB0_461
	v_mov_b32_e32 v230, v228
	v_mov_b32_e32 v229, 1.0

; __device__ __forceinline__ void qkt8_roll(f32x16& p0, f32x16& p1, const f32x16& negm, int kb, const bf16x8* qr) {
;   const int a0 = kb ^ (0 << 5); const bf16x8 x0 = lds_rd128<0>(a0), y0 = lds_rd128<8192>(a0);
;   const int a1 = kb ^ (1 << 5); const bf16x8 x1 = lds_rd128<0>(a1), y1 = lds_rd128<8192>(a1);
;   const int a2 = kb ^ (2 << 5); const bf16x8 x2 = lds_rd128<0>(a2), y2 = lds_rd128<8192>(a2);
;   asm volatile("s_waitcnt lgkmcnt(4)" ::: "memory"); SBAR_M();
;   p0 = __builtin_amdgcn_mfma_f32_32x32x16_bf16(x0, qr[0], negm, 0, 0, 0); p1 = __builtin_amdgcn_mfma_f32_32x32x16_bf16(y0, qr[0], negm, 0, 0, 0);
;   const int a3 = kb ^ (3 << 5); const bf16x8 x3 = lds_rd128<0>(a3), y3 = lds_rd128<8192>(a3);
;   asm volatile("s_waitcnt lgkmcnt(4)" ::: "memory"); SBAR_M();
;   p0 = __builtin_amdgcn_mfma_f32_32x32x16_bf16(x1, qr[1], p0, 0, 0, 0); p1 = __builtin_amdgcn_mfma_f32_32x32x16_bf16(y1, qr[1], p1, 0, 0, 0);
;   const int a4 = kb ^ (4 << 5); const bf16x8 x4 = lds_rd128<0>(a4), y4 = lds_rd128<8192>(a4);
;   asm volatile("s_waitcnt lgkmcnt(4)" ::: "memory"); SBAR_M();
;   p0 = __builtin_amdgcn_mfma_f32_32x32x16_bf16(x2, qr[2], p0, 0, 0, 0); p1 = __builtin_amdgcn_mfma_f32_32x32x16_bf16(y2, qr[2], p1, 0, 0, 0);
;   const int a5 = kb ^ (5 << 5); const bf16x8 x5 = lds_rd128<0>(a5), y5 = lds_rd128<8192>(a5);
;   asm volatile("s_waitcnt lgkmcnt(4)" ::: "memory"); SBAR_M();
;   p0 = __builtin_amdgcn_mfma_f32_32x32x16_bf16(x3, qr[3], p0, 0, 0, 0); p1 = __builtin_amdgcn_mfma_f32_32x32x16_bf16(y3, qr[3], p1, 0, 0, 0);
;   const int a6 = kb ^ (6 << 5); const bf16x8 x6 = lds_rd128<0>(a6), y6 = lds_rd128<8192>(a6);
;   asm volatile("s_waitcnt lgkmcnt(4)" ::: "memory"); SBAR_M();
;   p0 = __builtin_amdgcn_mfma_f32_32x32x16_bf16(x4, qr[4], p0, 0, 0, 0); p1 = __builtin_amdgcn_mfma_f32_32x32x16_bf16(y4, qr[4], p1, 0, 0, 0);
;   const int a7 = kb ^ (7 << 5); const bf16x8 x7 = lds_rd128<0>(a7), y7 = lds_rd128<8192>(a7);
;   asm volatile("s_waitcnt lgkmcnt(4)" ::: "memory"); SBAR_M();
;   p0 = __builtin_amdgcn_mfma_f32_32x32x16_bf16(x5, qr[5], p0, 0, 0, 0); p1 = __builtin_amdgcn_mfma_f32_32x32x16_bf16(y5, qr[5], p1, 0, 0, 0);
;   asm volatile("s_waitcnt lgkmcnt(2)" ::: "memory"); SBAR_M();
;   p0 = __builtin_amdgcn_mfma_f32_32x32x16_bf16(x6, qr[6], p0, 0, 0, 0); p1 = __builtin_amdgcn_mfma_f32_32x32x16_bf16(y6, qr[6], p1, 0, 0, 0);
.LBB0_453:
	v_xor_b32_e32 v66, 0x80000000, v228
	v_cndmask_b32_e64 v231, v66, v231, s[6:7]
	v_exp_f32_e32 v162, v114
	v_exp_f32_e32 v163, v116
	v_cmp_neq_f32_e64 s[6:7], v231, -v230
	s_cmp_eq_u64 s[6:7], 0
	s_cselect_b64 s[6:7], -1, 0
	s_cbranch_scc1 .Lmy_negm_skip_3
	v_cndmask_b32_e64 v97, -v230, v97, s[6:7]
	v_cndmask_b32_e64 v96, -v230, v96, s[6:7]
	v_cndmask_b32_e64 v95, -v230, v95, s[6:7]
	v_cndmask_b32_e64 v94, -v230, v94, s[6:7]
	v_cndmask_b32_e64 v93, -v230, v93, s[6:7]
	v_cndmask_b32_e64 v92, -v230, v92, s[6:7]
	v_cndmask_b32_e64 v91, -v230, v91, s[6:7]
	v_cndmask_b32_e64 v90, -v230, v90, s[6:7]
	v_cndmask_b32_e64 v89, -v230, v89, s[6:7]
	v_cndmask_b32_e64 v88, -v230, v88, s[6:7]
	v_cndmask_b32_e64 v87, -v230, v87, s[6:7]
	v_cndmask_b32_e64 v86, -v230, v86, s[6:7]
	v_cndmask_b32_e64 v85, -v230, v85, s[6:7]
	v_cndmask_b32_e64 v84, -v230, v84, s[6:7]
	v_cndmask_b32_e64 v83, -v230, v83, s[6:7]
	v_cndmask_b32_e64 v82, -v230, v82, s[6:7]
.Lmy_negm_skip_3:
	v_exp_f32_e32 v177, v115
	v_exp_f32_e32 v176, v117
	v_exp_f32_e32 v164, v118
	v_exp_f32_e32 v175, v119
	v_exp_f32_e32 v165, v120
	v_exp_f32_e32 v174, v121
	v_exp_f32_e32 v166, v122
	v_exp_f32_e32 v173, v123
	v_exp_f32_e32 v167, v124
	v_exp_f32_e32 v172, v125
	v_exp_f32_e32 v168, v126
	v_exp_f32_e32 v171, v127
	v_exp_f32_e32 v169, v128
	v_exp_f32_e32 v170, v129
	s_waitcnt lgkmcnt(0)
	s_barrier
	ds_read_b128 v[66:69], v200 offset:0
	ds_read_b128 v[232:235], v200 offset:0x2000
	ds_read_b128 v[236:239], v210 offset:0
	ds_read_b128 v[240:243], v210 offset:0x2000
	ds_read_b128 v[244:247], v211 offset:0
	ds_read_b128 v[248:251], v211 offset:0x2000
	s_waitcnt lgkmcnt(4)
	s_nop 0
	v_mfma_f32_32x32x16_bf16 v[114:129], v[66:69], v[158:161], v[82:97]
	v_mfma_f32_32x32x16_bf16 v[66:81], v[232:235], v[158:161], v[82:97]
	ds_read_b128 v[232:235], v212 offset:0
	ds_read_b128 v[192:195], v212 offset:0x2000
	s_waitcnt lgkmcnt(4)
	v_mfma_f32_32x32x16_bf16 v[114:129], v[236:239], v[154:157], v[114:129]
	ds_read_b128 v[236:239], v213 offset:0
	v_mfma_f32_32x32x16_bf16 v[66:81], v[240:243], v[154:157], v[66:81]
	ds_read_b128 v[240:243], v213 offset:0x2000
	s_waitcnt lgkmcnt(4)
	v_mfma_f32_32x32x16_bf16 v[114:129], v[244:247], v[150:153], v[114:129]
	ds_read_b128 v[244:247], v214 offset:0
	v_mfma_f32_32x32x16_bf16 v[66:81], v[248:251], v[150:153], v[66:81]
	ds_read_b128 v[248:251], v214 offset:0x2000
	s_waitcnt lgkmcnt(4)
	v_mfma_f32_32x32x16_bf16 v[114:129], v[232:235], v[146:149], v[114:129]
	v_mfma_f32_32x32x16_bf16 v[66:81], v[192:195], v[146:149], v[66:81]
	ds_read_b128 v[192:195], v215 offset:0
	ds_read_b128 v[232:235], v215 offset:0x2000
	s_waitcnt lgkmcnt(4)
	v_mfma_f32_32x32x16_bf16 v[114:129], v[236:239], v[142:145], v[114:129]
	ds_read_b128 v[236:239], v216 offset:0
	v_mfma_f32_32x32x16_bf16 v[66:81], v[240:243], v[142:145], v[66:81]
	ds_read_b128 v[240:243], v216 offset:0x2000
	s_waitcnt lgkmcnt(4)
	v_mfma_f32_32x32x16_bf16 v[114:129], v[244:247], v[138:141], v[114:129]
	s_waitcnt lgkmcnt(2)
	v_mfma_f32_32x32x16_bf16 v[66:81], v[248:251], v[138:141], v[66:81]
	v_mfma_f32_32x32x16_bf16 v[114:129], v[192:195], v[134:137], v[114:129]
	s_waitcnt lgkmcnt(0)
	v_mfma_f32_32x32x16_bf16 v[66:81], v[232:235], v[134:137], v[66:81]
	v_exp_f32_e32 v98, v98
	v_exp_f32_e32 v99, v99
	v_exp_f32_e32 v100, v100
	v_exp_f32_e32 v101, v101
	v_exp_f32_e32 v102, v102
	v_exp_f32_e32 v103, v103
	v_exp_f32_e32 v104, v104
	v_exp_f32_e32 v105, v105
	v_add_f32_e32 v192, v164, v162
	v_add_f32_e32 v193, v175, v177
	v_add_f32_e32 v194, v165, v163
	v_add_f32_e32 v195, v174, v176
	v_exp_f32_e32 v106, v106
	v_exp_f32_e32 v107, v107
	v_exp_f32_e32 v108, v108
	v_exp_f32_e32 v109, v109
	v_add_f32_e32 v192, v166, v192
	v_add_f32_e32 v193, v173, v193
	v_add_f32_e32 v194, v167, v194
	v_add_f32_e32 v195, v172, v195
	v_exp_f32_e32 v110, v110
	v_exp_f32_e32 v111, v111
	v_exp_f32_e32 v112, v112
	v_exp_f32_e32 v113, v113
	v_add_f32_e32 v192, v168, v192
	v_add_f32_e32 v193, v171, v193
	v_add_f32_e32 v194, v169, v194
	v_add_f32_e32 v195, v170, v195
	v_mfma_f32_32x32x16_bf16 v[114:129], v[236:239], v[130:133], v[114:129]
	v_add_f32_e32 v192, v98, v192
	v_add_f32_e32 v193, v193, v99
	v_add_f32_e32 v194, v194, v100
	v_add_f32_e32 v195, v195, v101
	v_add_f32_e32 v192, v102, v192
	v_add_f32_e32 v193, v103, v193
	v_add_f32_e32 v194, v104, v194
	v_mfma_f32_32x32x16_bf16 v[66:81], v[240:243], v[130:133], v[66:81]
	v_add_f32_e32 v195, v105, v195
	v_add_f32_e32 v192, v106, v192
	v_add_f32_e32 v193, v107, v193
	v_add_f32_e32 v194, v108, v194
	v_add_f32_e32 v195, v109, v195
	v_add_f32_e32 v192, v110, v192
	v_add_f32_e32 v193, v111, v193
	v_add_f32_e32 v194, v112, v194
	v_add_f32_e32 v195, v113, v195
	v_add_f32_e32 v192, v192, v193
	v_add_f32_e32 v193, v194, v195
	v_add_f32_e32 v232, v192, v193
	v_mov_b32_e32 v233, v232
	v_cvt_pk_bf16_f32 v162, v162, v177
	v_cvt_pk_bf16_f32 v163, v163, v176
	v_cvt_pk_bf16_f32 v164, v164, v175
	v_cvt_pk_bf16_f32 v165, v165, v174
	s_nop 1
	v_permlane32_swap_b32_e32 v232, v233
	v_cvt_pk_bf16_f32 v166, v166, v173
	v_cvt_pk_bf16_f32 v167, v167, v172
	v_cvt_pk_bf16_f32 v168, v168, v171
	v_cvt_pk_bf16_f32 v169, v169, v170
	v_cvt_pk_bf16_f32 v170, v98, v99
	v_cvt_pk_bf16_f32 v171, v100, v101
	v_cvt_pk_bf16_f32 v172, v102, v103
	v_cvt_pk_bf16_f32 v173, v104, v105
	v_cvt_pk_bf16_f32 v174, v106, v107
	v_cvt_pk_bf16_f32 v175, v108, v109
	v_cvt_pk_bf16_f32 v176, v110, v111
	v_cvt_pk_bf16_f32 v177, v112, v113
	s_nop 0
	v_add_co_u32_e32 v98, vcc, s72, v188
	s_nop 1
	v_addc_co_u32_e32 v99, vcc, 0, v189, vcc
	v_add_co_u32_e32 v102, vcc, s73, v188
	s_nop 1
	v_addc_co_u32_e32 v103, vcc, 0, v189, vcc
	v_add_co_u32_e32 v106, vcc, s33, v190
	global_load_dwordx4 v[98:101], v[98:99], off offset:2176
	s_nop 0
	global_load_dwordx4 v[102:105], v[102:103], off offset:2176
	v_addc_co_u32_e32 v107, vcc, 0, v191, vcc
	v_add_co_u32_e32 v110, vcc, s52, v190
	s_nop 1
	v_addc_co_u32_e32 v111, vcc, 0, v191, vcc
	global_load_dwordx4 v[106:109], v[106:107], off
	s_nop 0
	global_load_dwordx4 v[110:113], v[110:111], off
	ds_read_b64_tr_b16 v[188:189], v198 offset:0
	ds_read_b64_tr_b16 v[190:191], v198 offset:0x800
	ds_read_b64_tr_b16 v[192:193], v198 offset:0x1000
	ds_read_b64_tr_b16 v[194:195], v198 offset:0x1800
	ds_read_b64_tr_b16 v[234:235], v198 offset:0x2000
	ds_read_b64_tr_b16 v[236:237], v198 offset:0x2800
	ds_read_b64_tr_b16 v[238:239], v198 offset:0x3000
	ds_read_b64_tr_b16 v[240:241], v198 offset:0x3800
	ds_read_b64_tr_b16 v[242:243], v198 offset:0x200
	ds_read_b64_tr_b16 v[244:245], v198 offset:0xa00
	s_waitcnt lgkmcnt(8)
; __device__ __forceinline__ void pv_d0(f32x16* o, int vb, bf16x8 pa0, bf16x8 pa1, bf16x8 pa2, bf16x8 pa3) {
;     ...
;   const s16x4 l0 = tr_read<v_rd_off(0, 0, 0)>(vb), h0 = tr_read<v_rd_off(0, 0, 1)>(vb);
;   const s16x4 l1 = tr_read<v_rd_off(0, 1, 0)>(vb), h1 = tr_read<v_rd_off(0, 1, 1)>(vb);
;   const s16x4 l2 = tr_read<v_rd_off(0, 2, 0)>(vb), h2 = tr_read<v_rd_off(0, 2, 1)>(vb);
;   const s16x4 l3 = tr_read<v_rd_off(0, 3, 0)>(vb), h3 = tr_read<v_rd_off(0, 3, 1)>(vb);
;   const s16x4 l4 = tr_read<v_rd_off(1, 0, 0)>(vb), h4 = tr_read<v_rd_off(1, 0, 1)>(vb);
;   asm volatile("s_waitcnt lgkmcnt(8)" ::: "memory"); SBAR();
;   o[0] = __builtin_amdgcn_mfma_f32_32x32x16_bf16(pa0, PK(l0, h0), o[0], 0, 0, 0);
;   const s16x4 l5 = tr_read<v_rd_off(1, 1, 0)>(vb), h5 = tr_read<v_rd_off(1, 1, 1)>(vb);
;   asm volatile("s_waitcnt lgkmcnt(8)" ::: "memory"); SBAR();
;   o[0] = __builtin_amdgcn_mfma_f32_32x32x16_bf16(pa1, PK(l1, h1), o[0], 0, 0, 0);
;   const s16x4 l6 = tr_read<v_rd_off(1, 2, 0)>(vb), h6 = tr_read<v_rd_off(1, 2, 1)>(vb);
;   asm volatile("s_waitcnt lgkmcnt(8)" ::: "memory"); SBAR();
;   o[0] = __builtin_amdgcn_mfma_f32_32x32x16_bf16(pa2, PK(l2, h2), o[0], 0, 0, 0);
;   const s16x4 l7 = tr_read<v_rd_off(1, 3, 0)>(vb), h7 = tr_read<v_rd_off(1, 3, 1)>(vb);
;   asm volatile("s_waitcnt lgkmcnt(8)" ::: "memory"); SBAR();
;   o[0] = __builtin_amdgcn_mfma_f32_32x32x16_bf16(pa3, PK(l3, h3), o[0], 0, 0, 0);
;   const s16x4 l8 = tr_read<v_rd_off(2, 0, 0)>(vb), h8 = tr_read<v_rd_off(2, 0, 1)>(vb);
;   asm volatile("s_waitcnt lgkmcnt(8)" ::: "memory"); SBAR();
;   o[1] = __builtin_amdgcn_mfma_f32_32x32x16_bf16(pa0, PK(l4, h4), o[1], 0, 0, 0);
;   const s16x4 l9 = tr_read<v_rd_off(2, 1, 0)>(vb), h9 = tr_read<v_rd_off(2, 1, 1)>(vb);
;   asm volatile("s_waitcnt lgkmcnt(8)" ::: "memory"); SBAR();
;   o[1] = __builtin_amdgcn_mfma_f32_32x32x16_bf16(pa1, PK(l5, h5), o[1], 0, 0, 0);
;   const s16x4 l10 = tr_read<v_rd_off(2, 2, 0)>(vb), h10 = tr_read<v_rd_off(2, 2, 1)>(vb);
;   asm volatile("s_waitcnt lgkmcnt(8)" ::: "memory"); SBAR();
;   o[1] = __builtin_amdgcn_mfma_f32_32x32x16_bf16(pa2, PK(l6, h6), o[1], 0, 0, 0);
;   const s16x4 l11 = tr_read<v_rd_off(2, 3, 0)>(vb), h11 = tr_read<v_rd_off(2, 3, 1)>(vb);
;   asm volatile("s_waitcnt lgkmcnt(8)" ::: "memory"); SBAR();
;   o[1] = __builtin_amdgcn_mfma_f32_32x32x16_bf16(pa3, PK(l7, h7), o[1], 0, 0, 0);
	s_nop 0
	v_mfma_f32_32x32x16_bf16 v[2:17], v[162:165], v[188:191], v[2:17]
	ds_read_b64_tr_b16 v[188:189], v198 offset:0x1200
	ds_read_b64_tr_b16 v[190:191], v198 offset:0x1a00
	s_waitcnt lgkmcnt(8)
	v_mfma_f32_32x32x16_bf16 v[2:17], v[166:169], v[192:195], v[2:17]
	ds_read_b64_tr_b16 v[192:193], v198 offset:0x2200
	ds_read_b64_tr_b16 v[194:195], v198 offset:0x2a00
	s_waitcnt lgkmcnt(8)
	v_mfma_f32_32x32x16_bf16 v[2:17], v[170:173], v[234:237], v[2:17]
	ds_read_b64_tr_b16 v[234:235], v198 offset:0x3200
	ds_read_b64_tr_b16 v[236:237], v198 offset:0x3a00
	s_waitcnt lgkmcnt(8)
	v_mfma_f32_32x32x16_bf16 v[2:17], v[174:177], v[238:241], v[2:17]
	ds_read_b64_tr_b16 v[238:239], v198 offset:0x400
	ds_read_b64_tr_b16 v[240:241], v198 offset:0xc00
	s_waitcnt lgkmcnt(8)
	v_mfma_f32_32x32x16_bf16 v[50:65], v[162:165], v[242:245], v[50:65]
	ds_read_b64_tr_b16 v[242:243], v198 offset:0x1400
	ds_read_b64_tr_b16 v[244:245], v198 offset:0x1c00
	s_waitcnt lgkmcnt(8)
	v_mfma_f32_32x32x16_bf16 v[50:65], v[166:169], v[188:191], v[50:65]
	ds_read_b64_tr_b16 v[188:189], v198 offset:0x2400
	ds_read_b64_tr_b16 v[190:191], v198 offset:0x2c00
	s_waitcnt lgkmcnt(8)
	v_mfma_f32_32x32x16_bf16 v[50:65], v[170:173], v[192:195], v[50:65]
	ds_read_b64_tr_b16 v[192:193], v198 offset:0x3400
	ds_read_b64_tr_b16 v[194:195], v198 offset:0x3c00
	s_waitcnt lgkmcnt(8)
	v_mfma_f32_32x32x16_bf16 v[50:65], v[174:177], v[234:237], v[50:65]
	ds_read_b64_tr_b16 v[234:235], v198 offset:0x600
	ds_read_b64_tr_b16 v[236:237], v198 offset:0xe00
	s_waitcnt lgkmcnt(8)
	v_mfma_f32_32x32x16_bf16 v[34:49], v[162:165], v[238:241], v[34:49]
	ds_read_b64_tr_b16 v[238:239], v198 offset:0x1600
	ds_read_b64_tr_b16 v[240:241], v198 offset:0x1e00
	s_waitcnt lgkmcnt(8)
	v_mfma_f32_32x32x16_bf16 v[34:49], v[166:169], v[242:245], v[34:49]
	ds_read_b64_tr_b16 v[242:243], v198 offset:0x2600
	ds_read_b64_tr_b16 v[244:245], v198 offset:0x2e00
	s_waitcnt lgkmcnt(8)
	v_mfma_f32_32x32x16_bf16 v[34:49], v[170:173], v[188:191], v[34:49]
	ds_read_b64_tr_b16 v[188:189], v198 offset:0x3600
	ds_read_b64_tr_b16 v[190:191], v198 offset:0x3e00
	s_waitcnt lgkmcnt(8)
	v_mfma_f32_32x32x16_bf16 v[34:49], v[174:177], v[192:195], v[34:49]
	s_waitcnt lgkmcnt(6)
	v_mfma_f32_32x32x16_bf16 v[18:33], v[162:165], v[234:237], v[18:33]
	s_waitcnt lgkmcnt(4)
	v_mfma_f32_32x32x16_bf16 v[18:33], v[166:169], v[238:241], v[18:33]
	s_waitcnt lgkmcnt(2)
	v_mfma_f32_32x32x16_bf16 v[18:33], v[170:173], v[242:245], v[18:33]
	s_waitcnt lgkmcnt(0)
	v_max_f32_e32 v162, v114, v118
	v_max_f32_e32 v163, v115, v119
	v_max_f32_e32 v164, v117, v121
	v_max3_f32 v165, v116, v120, v124
	v_max3_f32 v164, v164, v125, v129
	v_max3_f32 v162, v162, v122, v126
	v_max3_f32 v163, v163, v123, v127
	v_max3_f32 v165, v165, v128, v68
	v_max3_f32 v164, v164, v69, v73
	v_max3_f32 v162, v162, v66, v70
	v_max3_f32 v163, v163, v67, v71
	v_max3_f32 v165, v165, v72, v76
	v_max3_f32 v164, v164, v77, v81
	v_mfma_f32_32x32x16_bf16 v[18:33], v[174:177], v[188:191], v[18:33]
	v_max3_f32 v162, v162, v74, v78
	v_max3_f32 v163, v163, v75, v79
	v_max3_f32 v164, v165, v80, v164
	v_max3_f32 v162, v162, v163, v164
	v_mov_b32_e32 v163, v162
	v_cmp_ge_f32_e32 vcc, s48, v163
	s_cmp_eq_u64 vcc, exec
	v_mov_b32_e32 v162, 1.0
	s_cbranch_scc0 .LBB0_462
	v_mov_b32_e32 v228, v230
